# RWKV staging: all LDS writes of a chunk deferred to the pair-sum block; wait for scan_done relocated there (staging computes the next chunk before waiting)
# speedup vs baseline: 1.0019x; 1.0019x over previous
.LBB0_654:
	s_and_b64 vcc, exec, s[0:1]
	s_cbranch_vccz .LBB0_676
	s_lshl_b32 s60, s50, 2
	s_add_i32 s60, s60, 0x255f0
	v_mov_b32_e32 v224, s60
	v_mov_b32_e32 v225, 0x25610
	v_bfe_u32 v214, v153, 4, 4
	v_and_b32_e32 v215, 15, v153
	v_mul_u32_u24_e32 v216, 48, v214
	v_add_u32_e32 v217, 0x11b00, v216
	v_mul_u32_u24_e32 v218, 0x900, v214
	v_lshl_add_u32 v218, v215, 4, v218
	v_add_u32_e32 v219, 0x11b00, v218
	v_lshlrev_b32_e32 v220, 7, v214
	v_lshl_add_u32 v220, v215, 2, v220
	v_add_u32_e32 v220, 0x9300, v220
	v_add_u32_e32 v221, 0x11b00, v220
	v_lshlrev_b32_e32 v222, 8, v214
	v_lshl_add_u32 v222, v215, 4, v222
	v_add_u32_e32 v222, 0x23600, v222
	v_add_u32_e32 v223, 0x1000, v222
	s_lshl_b32 s0, s2, 8
	s_and_b32 s4, s0, 0x4000
	s_add_u32 s12, s70, 0x4000000
	s_addc_u32 s13, s71, 0
	s_add_u32 s14, s70, 0x8000000
	s_addc_u32 s15, s71, 0
	s_add_u32 s20, s70, 0xc000000
	s_addc_u32 s21, s71, 0
	s_add_u32 s16, s78, 0x30000000
	s_addc_u32 s17, s79, 0
	s_add_u32 s18, s78, 0x34000000
	s_addc_u32 s19, s79, 0
	s_and_b32 s0, s2, 0x60
	s_lshl_b32 s24, s2, 2
	s_bfe_u32 s6, s2, 0x20003
	v_add_u32_e32 v20, 0xffffff00, v153
	s_and_b32 s1, s24, 28
	s_or_b32 s0, s6, s0
	v_ashrrev_i32_e32 v1, 4, v20
	s_or_b32 s25, s0, s1
	v_lshlrev_b32_e32 v26, 1, v1
	s_mov_b32 s5, 0
	s_lshl_b32 s0, s25, 4
	v_and_b32_e32 v23, 15, v153
	v_ashrrev_i32_e32 v27, 31, v26
	s_and_b32 s1, s0, 0x3c0
	v_lshlrev_b32_e32 v22, 2, v23
	v_lshl_add_u64 v[2:3], v[26:27], 0, s[4:5]
	v_or_b32_e32 v55, s1, v22
	v_lshlrev_b64 v[28:29], 10, v[2:3]
	v_or_b32_e32 v2, v28, v55
	v_mov_b32_e32 v3, v29
	v_lshlrev_b64 v[6:7], 1, v[2:3]
	v_lshl_add_u64 v[4:5], s[16:17], 0, v[6:7]
	v_lshl_add_u64 v[2:3], s[70:71], 0, v[6:7]
	global_load_dwordx2 v[8:9], v[4:5], off
	v_lshl_add_u64 v[4:5], s[12:13], 0, v[6:7]
	global_load_dwordx2 v[10:11], v[4:5], off
	v_lshl_add_u64 v[4:5], s[14:15], 0, v[6:7]
	global_load_dwordx2 v[12:13], v[2:3], off
	global_load_dwordx2 v[24:25], v[4:5], off
	global_load_dwordx2 v[14:15], v[2:3], off offset:2048
	v_lshl_add_u64 v[2:3], s[18:19], 0, v[6:7]
	v_or_b32_e32 v6, 0x800, v6
	v_lshl_add_u64 v[4:5], s[12:13], 0, v[6:7]
	global_load_dwordx2 v[16:17], v[4:5], off
	v_lshl_add_u64 v[4:5], s[16:17], 0, v[6:7]
	global_load_dwordx2 v[18:19], v[4:5], off
	global_load_dwordx2 v[38:39], v[2:3], off
	v_ashrrev_i32_e32 v4, 3, v20
	v_ashrrev_i32_e32 v5, 31, v4
	v_lshl_add_u64 v[30:31], s[4:5], 0, v[4:5]
	v_lshlrev_b64 v[32:33], 11, v[30:31]
	v_lshlrev_b32_e32 v2, 1, v153
	s_mov_b32 s7, s5
	v_lshl_add_u64 v[20:21], s[20:21], 0, v[32:33]
	s_and_b32 s0, s0, 48
	s_lshl_b32 s6, s1, 1
	s_mov_b32 s9, s5
	v_and_b32_e32 v58, 14, v2
	s_lshl_b32 s8, s0, 1
	v_lshl_add_u64 v[20:21], v[20:21], 0, s[6:7]
	v_mov_b32_e32 v3, 0
	v_lshlrev_b32_e32 v2, 1, v58
	v_lshl_add_u64 v[20:21], v[20:21], 0, s[8:9]
	v_lshl_add_u64 v[20:21], v[20:21], 0, v[2:3]
	v_lshl_add_u64 v[34:35], s[14:15], 0, v[6:7]
	v_lshl_add_u64 v[6:7], s[18:19], 0, v[6:7]
	global_load_dword v3, v[20:21], off
	global_load_dwordx2 v[40:41], v[34:35], off
	global_load_dwordx2 v[42:43], v[6:7], off
	v_lshl_add_u32 v59, v23, 4, 0
	s_movk_i32 s0, 0x900
	v_mad_i32_i24 v54, v1, s0, v59
	v_cmp_eq_u32_e64 s[0:1], 0, v23
	v_cmp_ne_u32_e32 vcc, 0, v23
	v_mul_i32_i24_e32 v23, 48, v1
	s_waitcnt vmcnt(0)
	v_cvt_f32_f16_e32 v6, v8
	v_cvt_f32_f16_sdwa v7, v8 dst_sel:DWORD dst_unused:UNUSED_PAD src0_sel:WORD_1
	v_cvt_f32_f16_e32 v20, v10
	v_cvt_f32_f16_sdwa v21, v10 dst_sel:DWORD dst_unused:UNUSED_PAD src0_sel:WORD_1
	v_cvt_f32_f16_e32 v44, v12
	v_cvt_f32_f16_sdwa v45, v12 dst_sel:DWORD dst_unused:UNUSED_PAD src0_sel:WORD_1
	v_cvt_f32_f16_e32 v46, v14
	v_cvt_f32_f16_sdwa v47, v14 dst_sel:DWORD dst_unused:UNUSED_PAD src0_sel:WORD_1
	v_cvt_f32_f16_e32 v10, v11
	v_cvt_f32_f16_sdwa v11, v11 dst_sel:DWORD dst_unused:UNUSED_PAD src0_sel:WORD_1
	v_cvt_f32_f16_e32 v48, v13
	v_cvt_f32_f16_sdwa v49, v13 dst_sel:DWORD dst_unused:UNUSED_PAD src0_sel:WORD_1
	v_cvt_f32_f16_e32 v50, v15
	v_cvt_f32_f16_sdwa v51, v15 dst_sel:DWORD dst_unused:UNUSED_PAD src0_sel:WORD_1
	v_cvt_f32_f16_e32 v12, v16
	v_cvt_f32_f16_sdwa v13, v16 dst_sel:DWORD dst_unused:UNUSED_PAD src0_sel:WORD_1
	v_cvt_f32_f16_e32 v14, v17
	v_cvt_f32_f16_sdwa v15, v17 dst_sel:DWORD dst_unused:UNUSED_PAD src0_sel:WORD_1
	v_cvt_f32_f16_e32 v52, v18
	v_cvt_f32_f16_sdwa v53, v18 dst_sel:DWORD dst_unused:UNUSED_PAD src0_sel:WORD_1
	v_cvt_f32_f16_e32 v56, v19
	v_cvt_f32_f16_sdwa v57, v19 dst_sel:DWORD dst_unused:UNUSED_PAD src0_sel:WORD_1
	v_cvt_f32_f16_e32 v8, v9
	v_cvt_f32_f16_sdwa v9, v9 dst_sel:DWORD dst_unused:UNUSED_PAD src0_sel:WORD_1
	v_pk_add_f32 v[20:21], v[20:21], 1.0 op_sel_hi:[1,0] neg_lo:[1,0] neg_hi:[1,0]
	v_pk_add_f32 v[60:61], v[10:11], 1.0 op_sel_hi:[1,0] neg_lo:[1,0] neg_hi:[1,0]
	v_pk_add_f32 v[62:63], v[12:13], 1.0 op_sel_hi:[1,0] neg_lo:[1,0] neg_hi:[1,0]
	v_pk_add_f32 v[64:65], v[14:15], 1.0 op_sel_hi:[1,0] neg_lo:[1,0] neg_hi:[1,0]
	v_pk_mul_f32 v[14:15], v[20:21], v[52:53]
	v_pk_mul_f32 v[16:17], v[60:61], v[56:57]
	v_pk_mul_f32 v[66:67], v[62:63], v[46:47]
	v_pk_mul_f32 v[68:69], v[64:65], v[50:51]
	v_pk_mul_f32 v[10:11], v[20:21], v[44:45]
	v_pk_mul_f32 v[12:13], v[60:61], v[48:49]
	v_pk_mul_f32 v[18:19], v[20:21], v[62:63]
	v_pk_mul_f32 v[34:35], v[20:21], v[66:67]
	v_pk_mul_f32 v[36:37], v[60:61], v[68:69]
	v_pk_mul_f32 v[20:21], v[60:61], v[64:65]
	v_mov_b32_e32 v120, v6
	v_mov_b32_e32 v121, v14
	v_mov_b32_e32 v122, v7
	v_mov_b32_e32 v123, v15
	v_mov_b32_e32 v124, v10
	v_mov_b32_e32 v125, v34
	v_mov_b32_e32 v126, v11
	v_mov_b32_e32 v127, v35
	v_mov_b32_e32 v128, v8
	v_mov_b32_e32 v129, v16
	v_mov_b32_e32 v130, v9
	v_mov_b32_e32 v131, v17
	v_mov_b32_e32 v132, v12
	v_mov_b32_e32 v133, v36
	v_mov_b32_e32 v134, v13
	v_mov_b32_e32 v135, v37
	v_mov_b32_e32 v240, v18
	v_mov_b32_e32 v241, v19
	v_mov_b32_e32 v242, v20
	v_mov_b32_e32 v243, v21
	v_cvt_f32_f16_e32 v14, v38
	v_cvt_f32_f16_sdwa v16, v38 dst_sel:DWORD dst_unused:UNUSED_PAD src0_sel:WORD_1
	v_cvt_f32_f16_e32 v15, v24
	v_cvt_f32_f16_sdwa v17, v24 dst_sel:DWORD dst_unused:UNUSED_PAD src0_sel:WORD_1
	v_cvt_f32_f16_e32 v21, v25
	v_cvt_f32_f16_sdwa v25, v25 dst_sel:DWORD dst_unused:UNUSED_PAD src0_sel:WORD_1
	v_cvt_f32_f16_e32 v20, v39
	v_cvt_f32_f16_sdwa v24, v39 dst_sel:DWORD dst_unused:UNUSED_PAD src0_sel:WORD_1
	v_mov_b32_e32 v8, v14
	v_mov_b32_e32 v9, v16
	v_mov_b32_e32 v6, v15
	v_mov_b32_e32 v7, v17
	v_pk_mul_f32 v[10:11], v[62:63], v[8:9]
	v_mov_b32_e32 v8, v21
	v_mov_b32_e32 v9, v25
	v_pk_mul_f32 v[6:7], v[62:63], v[6:7]
	v_pk_mul_f32 v[8:9], v[64:65], v[8:9]
	v_mov_b32_e32 v12, v20
	v_mov_b32_e32 v13, v24
	v_mov_b32_e32 v18, v53
	v_pk_mul_f32 v[12:13], v[64:65], v[12:13]
	v_mov_b32_e32 v182, v6
	v_mov_b32_e32 v183, v7
	v_mov_b32_e32 v184, v8
	v_mov_b32_e32 v185, v9
	v_mov_b32_e32 v244, v10
	v_mov_b32_e32 v245, v11
	v_mov_b32_e32 v246, v12
	v_mov_b32_e32 v247, v13
	v_pk_fma_f32 v[6:7], v[52:53], v[14:15], 0 op_sel_hi:[0,1,0]
	v_pk_fma_f32 v[6:7], v[18:19], v[16:17], v[6:7] op_sel_hi:[0,1,1]
	v_mov_b32_e32 v10, v45
	v_pk_fma_f32 v[18:19], v[44:45], v[14:15], 0 op_sel_hi:[0,1,0]
	v_pk_fma_f32 v[14:15], v[66:67], v[14:15], 0 op_sel_hi:[0,1,0]
	v_pk_fma_f32 v[10:11], v[10:11], v[16:17], v[18:19] op_sel_hi:[0,1,1]
	v_pk_fma_f32 v[14:15], v[66:67], v[16:17], v[14:15] op_sel:[1,0,0]
	v_mov_b32_e32 v34, v57
	v_pk_fma_f32 v[6:7], v[56:57], v[20:21], v[6:7] op_sel_hi:[0,1,1]
	v_mov_b32_e32 v12, v49
	v_pk_fma_f32 v[10:11], v[48:49], v[20:21], v[10:11] op_sel_hi:[0,1,1]
	v_pk_fma_f32 v[14:15], v[68:69], v[20:21], v[14:15] op_sel_hi:[0,1,1]
	v_pk_fma_f32 v[6:7], v[34:35], v[24:25], v[6:7] op_sel_hi:[0,1,1]
	v_pk_fma_f32 v[10:11], v[12:13], v[24:25], v[10:11] op_sel_hi:[0,1,1]
	v_pk_fma_f32 v[14:15], v[68:69], v[24:25], v[14:15] op_sel:[1,0,0]
	v_cvt_f32_f16_e32 v25, v40
	v_cvt_f32_f16_sdwa v35, v40 dst_sel:DWORD dst_unused:UNUSED_PAD src0_sel:WORD_1
	v_cvt_f32_f16_e32 v39, v41
	v_cvt_f32_f16_sdwa v41, v41 dst_sel:DWORD dst_unused:UNUSED_PAD src0_sel:WORD_1
	v_cvt_f32_f16_e32 v24, v42
	v_cvt_f32_f16_sdwa v34, v42 dst_sel:DWORD dst_unused:UNUSED_PAD src0_sel:WORD_1
	v_cvt_f32_f16_e32 v38, v43
	v_cvt_f32_f16_sdwa v40, v43 dst_sel:DWORD dst_unused:UNUSED_PAD src0_sel:WORD_1
	v_mov_b32_e32 v18, v25
	v_mov_b32_e32 v19, v35
	v_mov_b32_e32 v20, v39
	v_mov_b32_e32 v21, v41
	v_mov_b32_e32 v248, v18
	v_mov_b32_e32 v249, v19
	v_mov_b32_e32 v250, v20
	v_mov_b32_e32 v251, v21
	v_mov_b32_e32 v18, v24
	v_mov_b32_e32 v19, v34
	v_mov_b32_e32 v20, v38
	v_mov_b32_e32 v21, v40
	v_mov_b32_e32 v36, v47
	v_mov_b32_e32 v186, v18
	v_mov_b32_e32 v187, v19
	v_mov_b32_e32 v188, v20
	v_mov_b32_e32 v189, v21
	v_pk_fma_f32 v[18:19], v[46:47], v[24:25], 0 op_sel_hi:[0,1,0]
	v_pk_fma_f32 v[18:19], v[36:37], v[34:35], v[18:19] op_sel_hi:[0,1,1]
	v_mov_b32_e32 v42, v51
	v_pk_fma_f32 v[18:19], v[50:51], v[38:39], v[18:19] op_sel_hi:[0,1,1]
	v_pk_fma_f32 v[18:19], v[42:43], v[40:41], v[18:19] op_sel_hi:[0,1,1]
	v_mov_b32_dpp v8, v6 row_ror:8 row_mask:0xf bank_mask:0xf bound_ctrl:1
	v_mov_b32_dpp v9, v7 row_ror:8 row_mask:0xf bank_mask:0xf bound_ctrl:1
	v_mov_b32_dpp v12, v10 row_ror:8 row_mask:0xf bank_mask:0xf bound_ctrl:1
	v_mov_b32_dpp v13, v11 row_ror:8 row_mask:0xf bank_mask:0xf bound_ctrl:1
	v_mov_b32_dpp v16, v14 row_ror:8 row_mask:0xf bank_mask:0xf bound_ctrl:1
	v_mov_b32_dpp v17, v15 row_ror:8 row_mask:0xf bank_mask:0xf bound_ctrl:1
	v_mov_b32_dpp v20, v18 row_ror:8 row_mask:0xf bank_mask:0xf bound_ctrl:1
	v_mov_b32_dpp v21, v19 row_ror:8 row_mask:0xf bank_mask:0xf bound_ctrl:1
	v_pk_add_f32 v[6:7], v[6:7], v[8:9]
	v_pk_add_f32 v[10:11], v[10:11], v[12:13]
	v_pk_add_f32 v[14:15], v[14:15], v[16:17]
	v_pk_add_f32 v[18:19], v[18:19], v[20:21]
	v_mov_b32_dpp v8, v6 row_ror:4 row_mask:0xf bank_mask:0xf bound_ctrl:1
	v_mov_b32_dpp v9, v7 row_ror:4 row_mask:0xf bank_mask:0xf bound_ctrl:1
	v_mov_b32_dpp v12, v10 row_ror:4 row_mask:0xf bank_mask:0xf bound_ctrl:1
	v_mov_b32_dpp v13, v11 row_ror:4 row_mask:0xf bank_mask:0xf bound_ctrl:1
	v_mov_b32_dpp v16, v14 row_ror:4 row_mask:0xf bank_mask:0xf bound_ctrl:1
	v_mov_b32_dpp v17, v15 row_ror:4 row_mask:0xf bank_mask:0xf bound_ctrl:1
	v_mov_b32_dpp v20, v18 row_ror:4 row_mask:0xf bank_mask:0xf bound_ctrl:1
	v_mov_b32_dpp v21, v19 row_ror:4 row_mask:0xf bank_mask:0xf bound_ctrl:1
	v_pk_add_f32 v[6:7], v[6:7], v[8:9]
	v_pk_add_f32 v[10:11], v[10:11], v[12:13]
	v_pk_add_f32 v[14:15], v[14:15], v[16:17]
	v_pk_add_f32 v[18:19], v[18:19], v[20:21]
	v_mov_b32_dpp v8, v6 row_ror:2 row_mask:0xf bank_mask:0xf bound_ctrl:1
	v_mov_b32_dpp v9, v7 row_ror:2 row_mask:0xf bank_mask:0xf bound_ctrl:1
	v_mov_b32_dpp v12, v10 row_ror:2 row_mask:0xf bank_mask:0xf bound_ctrl:1
	v_mov_b32_dpp v13, v11 row_ror:2 row_mask:0xf bank_mask:0xf bound_ctrl:1
	v_mov_b32_dpp v16, v14 row_ror:2 row_mask:0xf bank_mask:0xf bound_ctrl:1
	v_mov_b32_dpp v17, v15 row_ror:2 row_mask:0xf bank_mask:0xf bound_ctrl:1
	v_mov_b32_dpp v20, v18 row_ror:2 row_mask:0xf bank_mask:0xf bound_ctrl:1
	v_mov_b32_dpp v21, v19 row_ror:2 row_mask:0xf bank_mask:0xf bound_ctrl:1
	v_pk_add_f32 v[6:7], v[6:7], v[8:9]
	v_pk_add_f32 v[10:11], v[10:11], v[12:13]
	v_pk_add_f32 v[14:15], v[14:15], v[16:17]
	v_pk_add_f32 v[18:19], v[18:19], v[20:21]
	v_mov_b32_dpp v8, v6 row_ror:1 row_mask:0xf bank_mask:0xf bound_ctrl:1
	v_mov_b32_dpp v9, v7 row_ror:1 row_mask:0xf bank_mask:0xf bound_ctrl:1
	v_mov_b32_dpp v12, v10 row_ror:1 row_mask:0xf bank_mask:0xf bound_ctrl:1
	v_mov_b32_dpp v13, v11 row_ror:1 row_mask:0xf bank_mask:0xf bound_ctrl:1
	v_mov_b32_dpp v16, v14 row_ror:1 row_mask:0xf bank_mask:0xf bound_ctrl:1
	v_mov_b32_dpp v17, v15 row_ror:1 row_mask:0xf bank_mask:0xf bound_ctrl:1
	v_mov_b32_dpp v20, v18 row_ror:1 row_mask:0xf bank_mask:0xf bound_ctrl:1
	v_mov_b32_dpp v21, v19 row_ror:1 row_mask:0xf bank_mask:0xf bound_ctrl:1
	s_and_saveexec_b64 s[10:11], vcc
	s_xor_b64 s[10:11], exec, s[10:11]
	v_mul_i32_i24_e32 v23, 48, v1
	s_or_saveexec_b64 s[10:11], s[10:11]
	v_mul_i32_i24_e32 v62, 0x900, v1
	s_xor_b64 exec, exec, s[10:11]
	s_cbranch_execz .LBB0_659
	v_pk_add_f32 v[6:7], v[6:7], v[8:9]
	v_pk_add_f32 v[8:9], v[10:11], v[12:13]
	s_mov_b32 s22, 0x3d800000
	v_pk_mul_f32 v[8:9], v[8:9], s[22:23] op_sel_hi:[1,0]
	v_mad_i32_i24 v1, v1, 48, 0
	ds_write_b128 v1, v[6:9] offset:36864
	v_pk_add_f32 v[6:7], v[14:15], v[16:17]
	v_pk_add_f32 v[8:9], v[18:19], v[20:21]
	v_pk_mul_f32 v[6:7], v[6:7], s[22:23] op_sel_hi:[1,0]
	v_pk_mul_f32 v[8:9], v[8:9], s[22:23] op_sel_hi:[1,0]
	ds_write_b128 v1, v[6:9] offset:36880
.LBB0_659:
	s_or_b64 exec, exec, s[10:11]
	s_or_b32 s22, s4, 32
	s_mov_b32 s23, s5
	v_lshl_add_u64 v[6:7], s[22:23], 0, v[26:27]
	v_lshlrev_b64 v[6:7], 11, v[6:7]
	v_lshlrev_b32_e32 v25, 1, v55
	v_or_b32_e32 v6, v6, v25
	v_lshl_add_u64 v[8:9], s[70:71], 0, v[6:7]
	v_lshl_add_u64 v[10:11], s[12:13], 0, v[6:7]
	v_lshl_add_u64 v[12:13], s[14:15], 0, v[6:7]
	v_lshl_add_u64 v[14:15], s[16:17], 0, v[6:7]
	v_lshl_add_u64 v[16:17], s[18:19], 0, v[6:7]
	v_or_b32_e32 v6, 0x800, v6
	global_load_dwordx2 v[10:11], v[10:11], off
	v_lshl_add_u64 v[18:19], s[12:13], 0, v[6:7]
	global_load_dwordx2 v[14:15], v[14:15], off
	s_nop 0
	global_load_dwordx2 v[18:19], v[18:19], off
	s_nop 0
	global_load_dwordx2 v[20:21], v[8:9], off
	global_load_dwordx2 v[56:57], v[12:13], off
	s_nop 0
	global_load_dwordx2 v[12:13], v[8:9], off offset:2048
	v_lshl_add_u64 v[8:9], s[16:17], 0, v[6:7]
	global_load_dwordx2 v[64:65], v[8:9], off
	global_load_dwordx2 v[68:69], v[16:17], off
	v_cvt_f32_f16_sdwa v9, v3 dst_sel:DWORD dst_unused:UNUSED_PAD src0_sel:WORD_1
	v_cvt_f32_f16_e32 v8, v3
	s_or_b32 s26, s4, 64
	s_mov_b32 s27, s5
	v_lshl_add_u64 v[34:35], s[22:23], 0, v[4:5]
	v_lshl_add_u64 v[36:37], s[26:27], 0, v[26:27]
	v_lshlrev_b32_e32 v1, 6, v4
	s_mov_b32 s11, 0
	v_lshlrev_b32_e32 v24, 2, v58
	v_lshl_add_u64 v[38:39], s[26:27], 0, v[4:5]
	v_lshlrev_b64 v[34:35], 11, v[34:35]
	v_lshlrev_b64 v[36:37], 11, v[36:37]
	v_add3_u32 v1, 0, v1, v24
	s_mov_b32 s7, s11
	v_lshlrev_b64 v[38:39], 11, v[38:39]
	v_lshl_add_u64 v[34:35], s[20:21], 0, v[34:35]
	v_or_b32_e32 v36, v36, v25
	v_lshl_add_u64 v[38:39], s[20:21], 0, v[38:39]
	ds_write_b64 v1, v[8:9] offset:37632
	ds_read_b128 v[198:201], v216 offset:36864
	ds_read_b128 v[202:205], v216 offset:36880
	ds_read2_b32 v[206:207], v220 offset1:16
	s_waitcnt lgkmcnt(0)
	v_mul_f32_e32 v210, 0x41800000, v200
	v_mul_f32_e32 v211, 0x41800000, v202
	v_mul_f32_e32 v212, 0x41800000, v204
	v_fma_f32 v213, -v204, v199, v203
	v_fma_f32 v121, -v198, v120, v121
	v_fma_f32 v124, -v210, v120, v124
	v_fma_f32 v125, -v211, v120, v125
	v_fma_f32 v123, -v198, v122, v123
	v_fma_f32 v126, -v210, v122, v126
	v_fma_f32 v127, -v211, v122, v127
	v_fma_f32 v129, -v198, v128, v129
	v_fma_f32 v132, -v210, v128, v132
	v_fma_f32 v133, -v211, v128, v133
	v_fma_f32 v131, -v198, v130, v131
	v_fma_f32 v134, -v210, v130, v134
	v_fma_f32 v135, -v211, v130, v135
	v_fma_f32 v182, -v199, v186, v182
	v_fma_f32 v183, -v199, v187, v183
	v_fma_f32 v184, -v199, v188, v184
	v_fma_f32 v185, -v199, v189, v185
	v_fma_f32 v125, -v212, v121, v125
	v_fma_f32 v127, -v212, v123, v127
	v_fma_f32 v133, -v212, v129, v133
	v_fma_f32 v135, -v212, v131, v135
	v_mul_f32_e32 v208, v206, v201
	v_mul_f32_e32 v209, v206, v213
	ds_write_b128 v218, v[120:123]
	v_fmac_f32_e32 v209, v207, v205
	ds_write_b128 v218, v[124:127] offset:256
	ds_write_b128 v218, v[128:131] offset:512
	ds_write_b128 v218, v[132:135] offset:768
	ds_write_b128 v218, v[240:243] offset:1024
	ds_write_b128 v218, v[182:185] offset:1280
	ds_write_b128 v218, v[244:247] offset:1536
	ds_write_b128 v218, v[248:251] offset:1792
	ds_write_b128 v218, v[186:189] offset:2048
	ds_write_b128 v222, v[206:209]
	v_lshl_add_u64 v[8:9], v[34:35], 0, s[6:7]
	v_lshl_add_u64 v[34:35], s[14:15], 0, v[36:37]
	v_lshl_add_u64 v[40:41], s[16:17], 0, v[36:37]
	v_lshl_add_u64 v[50:51], s[14:15], 0, v[6:7]
	v_lshl_add_u64 v[46:47], s[18:19], 0, v[36:37]
	v_lshl_add_u64 v[48:49], v[38:39], 0, s[6:7]
	v_lshl_add_u64 v[6:7], s[18:19], 0, v[6:7]
	global_load_dwordx2 v[38:39], v[34:35], off
	global_load_dwordx2 v[42:43], v[40:41], off
	s_nop 0
	global_load_dwordx2 v[40:41], v[46:47], off
	global_load_dwordx2 v[70:71], v[50:51], off
	global_load_dwordx2 v[72:73], v[6:7], off
	s_add_i32 s10, 0, 0x11b00
	s_mov_b32 s9, s11
	v_lshl_add_u64 v[16:17], s[70:71], 0, v[36:37]
	v_lshl_add_u64 v[44:45], s[12:13], 0, v[36:37]
	v_or_b32_e32 v36, 0x800, v36
	v_mov_b32_e32 v3, 0
	v_lshl_add_u32 v22, v22, 2, s10
	v_lshl_add_u64 v[8:9], v[8:9], 0, s[8:9]
	v_lshl_add_u64 v[34:35], s[12:13], 0, v[36:37]
	v_lshl_add_u64 v[46:47], s[14:15], 0, v[36:37]
	v_lshl_add_u64 v[66:67], s[16:17], 0, v[36:37]
	v_lshl_add_u64 v[36:37], s[18:19], 0, v[36:37]
	v_lshl_add_u64 v[48:49], v[48:49], 0, s[8:9]
	v_add_u32_e32 v76, v22, v62
	v_lshl_add_u64 v[6:7], v[8:9], 0, v[2:3]
	global_load_dwordx2 v[52:53], v[34:35], off
	s_nop 0
	global_load_dwordx2 v[34:35], v[46:47], off
	s_nop 0
	global_load_dwordx2 v[46:47], v[66:67], off
	s_nop 0
	global_load_dwordx2 v[36:37], v[36:37], off
	v_lshl_add_u64 v[8:9], v[48:49], 0, v[2:3]
	global_load_dwordx2 v[50:51], v[44:45], off
	global_load_dword v22, v[6:7], off
	global_load_dwordx2 v[48:49], v[16:17], off
	s_nop 0
	global_load_dwordx2 v[44:45], v[16:17], off offset:2048
	global_load_dword v61, v[8:9], off
	s_waitcnt lgkmcnt(0)
	s_mov_b32 s61, 1
	s_waitcnt lgkmcnt(0)
	v_mov_b32_e32 v226, s61
	s_mov_b64 s[58:59], exec
	s_mov_b64 exec, 1
	ds_write_b32 v224, v226
	s_mov_b64 exec, s[58:59]
	s_waitcnt lgkmcnt(0)
	s_barrier
	v_lshlrev_b32_e32 v60, 4, v4
	v_add_u32_e32 v77, 0, v23
	s_waitcnt vmcnt(19)
	v_cvt_f32_f16_e32 v16, v18
	v_cvt_f32_f16_sdwa v17, v18 dst_sel:DWORD dst_unused:UNUSED_PAD src0_sel:WORD_1
	v_cvt_f32_f16_e32 v8, v10
	v_cvt_f32_f16_sdwa v9, v10 dst_sel:DWORD dst_unused:UNUSED_PAD src0_sel:WORD_1
	v_cvt_f32_f16_e32 v10, v11
	v_pk_add_f32 v[78:79], v[16:17], 1.0 op_sel_hi:[1,0] neg_lo:[1,0] neg_hi:[1,0]
	v_cvt_f32_f16_e32 v16, v19
	v_cvt_f32_f16_sdwa v17, v19 dst_sel:DWORD dst_unused:UNUSED_PAD src0_sel:WORD_1
	v_cvt_f32_f16_sdwa v11, v11 dst_sel:DWORD dst_unused:UNUSED_PAD src0_sel:WORD_1
	s_waitcnt vmcnt(16)
	v_cvt_f32_f16_e32 v80, v12
	v_cvt_f32_f16_sdwa v81, v12 dst_sel:DWORD dst_unused:UNUSED_PAD src0_sel:WORD_1
	s_waitcnt vmcnt(15)
	v_cvt_f32_f16_e32 v82, v64
	v_cvt_f32_f16_sdwa v83, v64 dst_sel:DWORD dst_unused:UNUSED_PAD src0_sel:WORD_1
	v_cvt_f32_f16_e32 v92, v65
	v_cvt_f32_f16_sdwa v93, v65 dst_sel:DWORD dst_unused:UNUSED_PAD src0_sel:WORD_1
	v_cvt_f32_f16_e32 v94, v13
	v_cvt_f32_f16_sdwa v95, v13 dst_sel:DWORD dst_unused:UNUSED_PAD src0_sel:WORD_1
	v_cvt_f32_f16_e32 v6, v14
	v_cvt_f32_f16_sdwa v7, v14 dst_sel:DWORD dst_unused:UNUSED_PAD src0_sel:WORD_1
	v_cvt_f32_f16_e32 v74, v20
	v_pk_add_f32 v[66:67], v[8:9], 1.0 op_sel_hi:[1,0] neg_lo:[1,0] neg_hi:[1,0]
	v_cvt_f32_f16_sdwa v75, v20 dst_sel:DWORD dst_unused:UNUSED_PAD src0_sel:WORD_1
	v_cvt_f32_f16_e32 v8, v15
	v_cvt_f32_f16_sdwa v9, v15 dst_sel:DWORD dst_unused:UNUSED_PAD src0_sel:WORD_1
	v_cvt_f32_f16_e32 v90, v21
	v_cvt_f32_f16_sdwa v91, v21 dst_sel:DWORD dst_unused:UNUSED_PAD src0_sel:WORD_1
	v_pk_add_f32 v[86:87], v[16:17], 1.0 op_sel_hi:[1,0] neg_lo:[1,0] neg_hi:[1,0]
	v_pk_add_f32 v[88:89], v[10:11], 1.0 op_sel_hi:[1,0] neg_lo:[1,0] neg_hi:[1,0]
	v_pk_mul_f32 v[84:85], v[78:79], v[80:81]
	v_pk_mul_f32 v[14:15], v[66:67], v[82:83]
	v_pk_mul_f32 v[16:17], v[88:89], v[92:93]
	v_pk_mul_f32 v[96:97], v[86:87], v[94:95]
	v_pk_mul_f32 v[10:11], v[66:67], v[74:75]
	v_pk_mul_f32 v[12:13], v[88:89], v[90:91]
	v_pk_mul_f32 v[18:19], v[66:67], v[84:85]
	v_pk_mul_f32 v[20:21], v[88:89], v[96:97]
	v_pk_mul_f32 v[64:65], v[66:67], v[78:79]
	v_pk_mul_f32 v[66:67], v[88:89], v[86:87]
	v_mov_b32_e32 v120, v6
	v_mov_b32_e32 v121, v14
	v_mov_b32_e32 v122, v7
	v_mov_b32_e32 v123, v15
	v_mov_b32_e32 v124, v10
	v_mov_b32_e32 v125, v18
	v_mov_b32_e32 v126, v11
	v_mov_b32_e32 v127, v19
	v_mov_b32_e32 v128, v8
	v_mov_b32_e32 v129, v16
	v_mov_b32_e32 v130, v9
	v_mov_b32_e32 v131, v17
	v_mov_b32_e32 v132, v12
	v_mov_b32_e32 v133, v20
	v_mov_b32_e32 v134, v13
	v_mov_b32_e32 v135, v21
	v_mov_b32_e32 v240, v64
	v_mov_b32_e32 v241, v65
	v_mov_b32_e32 v242, v66
	v_mov_b32_e32 v243, v67
	s_waitcnt vmcnt(14)
	v_cvt_f32_f16_e32 v14, v68
	v_cvt_f32_f16_sdwa v16, v68 dst_sel:DWORD dst_unused:UNUSED_PAD src0_sel:WORD_1
	v_cvt_f32_f16_e32 v15, v56
	v_cvt_f32_f16_sdwa v17, v56 dst_sel:DWORD dst_unused:UNUSED_PAD src0_sel:WORD_1
	v_cvt_f32_f16_e32 v21, v57
	v_cvt_f32_f16_sdwa v57, v57 dst_sel:DWORD dst_unused:UNUSED_PAD src0_sel:WORD_1
	v_cvt_f32_f16_e32 v20, v69
	v_cvt_f32_f16_sdwa v56, v69 dst_sel:DWORD dst_unused:UNUSED_PAD src0_sel:WORD_1
	v_mov_b32_e32 v8, v14
	v_mov_b32_e32 v9, v16
	v_mov_b32_e32 v6, v15
	v_mov_b32_e32 v7, v17
	v_pk_mul_f32 v[10:11], v[78:79], v[8:9]
	v_mov_b32_e32 v8, v21
	v_mov_b32_e32 v9, v57
	v_pk_mul_f32 v[6:7], v[78:79], v[6:7]
	v_pk_mul_f32 v[8:9], v[86:87], v[8:9]
	v_mov_b32_e32 v12, v20
	v_mov_b32_e32 v13, v56
	v_mov_b32_e32 v18, v83
	v_pk_mul_f32 v[12:13], v[86:87], v[12:13]
	v_mov_b32_e32 v182, v6
	v_mov_b32_e32 v183, v7
	v_mov_b32_e32 v184, v8
	v_mov_b32_e32 v185, v9
	v_mov_b32_e32 v244, v10
	v_mov_b32_e32 v245, v11
	v_mov_b32_e32 v246, v12
	v_mov_b32_e32 v247, v13
	v_pk_fma_f32 v[6:7], v[82:83], v[14:15], 0 op_sel_hi:[0,1,0]
	v_pk_fma_f32 v[6:7], v[18:19], v[16:17], v[6:7] op_sel_hi:[0,1,1]
	v_mov_b32_e32 v10, v75
	v_pk_fma_f32 v[18:19], v[74:75], v[14:15], 0 op_sel_hi:[0,1,0]
	v_pk_fma_f32 v[14:15], v[84:85], v[14:15], 0 op_sel_hi:[0,1,0]
	v_pk_fma_f32 v[10:11], v[10:11], v[16:17], v[18:19] op_sel_hi:[0,1,1]
	v_pk_fma_f32 v[14:15], v[84:85], v[16:17], v[14:15] op_sel:[1,0,0]
	v_mov_b32_e32 v54, v93
	v_pk_fma_f32 v[6:7], v[92:93], v[20:21], v[6:7] op_sel_hi:[0,1,1]
	v_mov_b32_e32 v12, v91
	v_pk_fma_f32 v[10:11], v[90:91], v[20:21], v[10:11] op_sel_hi:[0,1,1]
	v_pk_fma_f32 v[14:15], v[96:97], v[20:21], v[14:15] op_sel_hi:[0,1,1]
	v_pk_fma_f32 v[6:7], v[54:55], v[56:57], v[6:7] op_sel_hi:[0,1,1]
	v_pk_fma_f32 v[10:11], v[12:13], v[56:57], v[10:11] op_sel_hi:[0,1,1]
	v_pk_fma_f32 v[14:15], v[96:97], v[56:57], v[14:15] op_sel:[1,0,0]
	s_waitcnt vmcnt(10)
	v_cvt_f32_f16_e32 v57, v70
	v_cvt_f32_f16_sdwa v65, v70 dst_sel:DWORD dst_unused:UNUSED_PAD src0_sel:WORD_1
	v_cvt_f32_f16_e32 v67, v71
	v_cvt_f32_f16_sdwa v69, v71 dst_sel:DWORD dst_unused:UNUSED_PAD src0_sel:WORD_1
	s_waitcnt vmcnt(9)
	v_cvt_f32_f16_e32 v56, v72
	v_cvt_f32_f16_sdwa v64, v72 dst_sel:DWORD dst_unused:UNUSED_PAD src0_sel:WORD_1
	v_cvt_f32_f16_e32 v66, v73
	v_cvt_f32_f16_sdwa v68, v73 dst_sel:DWORD dst_unused:UNUSED_PAD src0_sel:WORD_1
	v_mov_b32_e32 v18, v57
	v_mov_b32_e32 v19, v65
	v_mov_b32_e32 v20, v67
	v_mov_b32_e32 v21, v69
	v_mov_b32_e32 v248, v18
	v_mov_b32_e32 v249, v19
	v_mov_b32_e32 v250, v20
	v_mov_b32_e32 v251, v21
	v_mov_b32_e32 v18, v56
	v_mov_b32_e32 v19, v64
	v_mov_b32_e32 v20, v66
	v_mov_b32_e32 v21, v68
	v_mov_b32_e32 v54, v81
	v_mov_b32_e32 v186, v18
	v_mov_b32_e32 v187, v19
	v_mov_b32_e32 v188, v20
	v_mov_b32_e32 v189, v21
	v_pk_fma_f32 v[18:19], v[80:81], v[56:57], 0 op_sel_hi:[0,1,0]
	v_pk_fma_f32 v[18:19], v[54:55], v[64:65], v[18:19] op_sel_hi:[0,1,1]
	v_mov_b32_e32 v70, v95
	v_pk_fma_f32 v[18:19], v[94:95], v[66:67], v[18:19] op_sel_hi:[0,1,1]
	v_pk_fma_f32 v[18:19], v[70:71], v[68:69], v[18:19] op_sel_hi:[0,1,1]
	v_mov_b32_dpp v8, v6 row_ror:8 row_mask:0xf bank_mask:0xf bound_ctrl:1
	v_mov_b32_dpp v9, v7 row_ror:8 row_mask:0xf bank_mask:0xf bound_ctrl:1
	v_mov_b32_dpp v12, v10 row_ror:8 row_mask:0xf bank_mask:0xf bound_ctrl:1
	v_mov_b32_dpp v13, v11 row_ror:8 row_mask:0xf bank_mask:0xf bound_ctrl:1
	v_mov_b32_dpp v16, v14 row_ror:8 row_mask:0xf bank_mask:0xf bound_ctrl:1
	v_mov_b32_dpp v17, v15 row_ror:8 row_mask:0xf bank_mask:0xf bound_ctrl:1
	v_mov_b32_dpp v20, v18 row_ror:8 row_mask:0xf bank_mask:0xf bound_ctrl:1
	v_mov_b32_dpp v21, v19 row_ror:8 row_mask:0xf bank_mask:0xf bound_ctrl:1
	v_pk_add_f32 v[6:7], v[6:7], v[8:9]
	v_pk_add_f32 v[10:11], v[10:11], v[12:13]
	v_pk_add_f32 v[14:15], v[14:15], v[16:17]
	v_pk_add_f32 v[18:19], v[18:19], v[20:21]
	v_mov_b32_dpp v8, v6 row_ror:4 row_mask:0xf bank_mask:0xf bound_ctrl:1
	v_mov_b32_dpp v9, v7 row_ror:4 row_mask:0xf bank_mask:0xf bound_ctrl:1
	v_mov_b32_dpp v12, v10 row_ror:4 row_mask:0xf bank_mask:0xf bound_ctrl:1
	v_mov_b32_dpp v13, v11 row_ror:4 row_mask:0xf bank_mask:0xf bound_ctrl:1
	v_mov_b32_dpp v16, v14 row_ror:4 row_mask:0xf bank_mask:0xf bound_ctrl:1
	v_mov_b32_dpp v17, v15 row_ror:4 row_mask:0xf bank_mask:0xf bound_ctrl:1
	v_mov_b32_dpp v20, v18 row_ror:4 row_mask:0xf bank_mask:0xf bound_ctrl:1
	v_mov_b32_dpp v21, v19 row_ror:4 row_mask:0xf bank_mask:0xf bound_ctrl:1
	v_pk_add_f32 v[6:7], v[6:7], v[8:9]
	v_pk_add_f32 v[10:11], v[10:11], v[12:13]
	v_pk_add_f32 v[14:15], v[14:15], v[16:17]
	v_pk_add_f32 v[18:19], v[18:19], v[20:21]
	v_mov_b32_dpp v8, v6 row_ror:2 row_mask:0xf bank_mask:0xf bound_ctrl:1
	v_mov_b32_dpp v9, v7 row_ror:2 row_mask:0xf bank_mask:0xf bound_ctrl:1
	v_mov_b32_dpp v12, v10 row_ror:2 row_mask:0xf bank_mask:0xf bound_ctrl:1
	v_mov_b32_dpp v13, v11 row_ror:2 row_mask:0xf bank_mask:0xf bound_ctrl:1
	v_mov_b32_dpp v16, v14 row_ror:2 row_mask:0xf bank_mask:0xf bound_ctrl:1
	v_mov_b32_dpp v17, v15 row_ror:2 row_mask:0xf bank_mask:0xf bound_ctrl:1
	v_mov_b32_dpp v20, v18 row_ror:2 row_mask:0xf bank_mask:0xf bound_ctrl:1
	v_mov_b32_dpp v21, v19 row_ror:2 row_mask:0xf bank_mask:0xf bound_ctrl:1
	v_pk_add_f32 v[6:7], v[6:7], v[8:9]
	v_pk_add_f32 v[10:11], v[10:11], v[12:13]
	v_pk_add_f32 v[14:15], v[14:15], v[16:17]
	v_pk_add_f32 v[18:19], v[18:19], v[20:21]
	v_mov_b32_dpp v8, v6 row_ror:1 row_mask:0xf bank_mask:0xf bound_ctrl:1
	v_mov_b32_dpp v9, v7 row_ror:1 row_mask:0xf bank_mask:0xf bound_ctrl:1
	v_mov_b32_dpp v12, v10 row_ror:1 row_mask:0xf bank_mask:0xf bound_ctrl:1
	v_mov_b32_dpp v13, v11 row_ror:1 row_mask:0xf bank_mask:0xf bound_ctrl:1
	v_mov_b32_dpp v16, v14 row_ror:1 row_mask:0xf bank_mask:0xf bound_ctrl:1
	v_mov_b32_dpp v17, v15 row_ror:1 row_mask:0xf bank_mask:0xf bound_ctrl:1
	v_mov_b32_dpp v20, v18 row_ror:1 row_mask:0xf bank_mask:0xf bound_ctrl:1
	v_mov_b32_dpp v21, v19 row_ror:1 row_mask:0xf bank_mask:0xf bound_ctrl:1
	s_and_saveexec_b64 s[22:23], s[0:1]
	s_cbranch_execz .LBB0_661
	v_pk_add_f32 v[6:7], v[6:7], v[8:9]
	v_pk_add_f32 v[8:9], v[10:11], v[12:13]
	s_mov_b32 s10, 0x3d800000
	v_pk_mul_f32 v[8:9], v[8:9], s[10:11] op_sel_hi:[1,0]
	v_add_u32_e32 v10, 0x1ab00, v77
	ds_write_b128 v10, v[6:9]
	v_pk_add_f32 v[6:7], v[14:15], v[16:17]
	v_pk_add_f32 v[8:9], v[18:19], v[20:21]
	v_pk_mul_f32 v[6:7], v[6:7], s[10:11] op_sel_hi:[1,0]
	v_pk_mul_f32 v[8:9], v[8:9], s[10:11] op_sel_hi:[1,0]
	ds_write_b128 v10, v[6:9] offset:16
.LBB0_661:
	s_or_b64 exec, exec, s[22:23]
	v_lshlrev_b32_e32 v6, 2, v60
	s_add_i32 s7, 0, 0x1ae00
	v_add3_u32 v78, s7, v6, v24
	s_add_u32 s7, s20, s6
	s_addc_u32 s9, s21, 0
	s_add_u32 s20, s7, s8
	s_waitcnt vmcnt(3)
	v_cvt_f32_f16_sdwa v7, v22 dst_sel:DWORD dst_unused:UNUSED_PAD src0_sel:WORD_1
	v_cvt_f32_f16_e32 v6, v22
	s_addc_u32 s21, s9, 0
	v_lshl_add_u64 v[56:57], s[20:21], 0, v[2:3]
	s_mov_b64 s[20:21], 0x18000
	v_or_b32_e32 v54, 0x400, v55
	v_lshl_add_u64 v[16:17], v[28:29], 0, s[20:21]
	ds_write_b64 v78, v[6:7]
	ds_read_b128 v[198:201], v217 offset:36864
	ds_read_b128 v[202:205], v217 offset:36880
	ds_read2_b32 v[206:207], v221 offset1:16
	s_waitcnt lgkmcnt(0)
	v_mul_f32_e32 v210, 0x41800000, v200
	v_mul_f32_e32 v211, 0x41800000, v202
	v_mul_f32_e32 v212, 0x41800000, v204
	v_fma_f32 v213, -v204, v199, v203
	v_fma_f32 v121, -v198, v120, v121
	v_fma_f32 v124, -v210, v120, v124
	v_fma_f32 v125, -v211, v120, v125
	v_fma_f32 v123, -v198, v122, v123
	v_fma_f32 v126, -v210, v122, v126
	v_fma_f32 v127, -v211, v122, v127
	v_fma_f32 v129, -v198, v128, v129
	v_fma_f32 v132, -v210, v128, v132
	v_fma_f32 v133, -v211, v128, v133
	v_fma_f32 v131, -v198, v130, v131
	v_fma_f32 v134, -v210, v130, v134
	v_fma_f32 v135, -v211, v130, v135
	v_fma_f32 v182, -v199, v186, v182
	v_fma_f32 v183, -v199, v187, v183
	v_fma_f32 v184, -v199, v188, v184
	v_fma_f32 v185, -v199, v189, v185
	v_fma_f32 v125, -v212, v121, v125
	v_fma_f32 v127, -v212, v123, v127
	v_fma_f32 v133, -v212, v129, v133
	v_fma_f32 v135, -v212, v131, v135
	v_mul_f32_e32 v208, v206, v201
	v_mul_f32_e32 v209, v206, v213
	ds_write_b128 v219, v[120:123]
	v_fmac_f32_e32 v209, v207, v205
	ds_write_b128 v219, v[124:127] offset:256
	ds_write_b128 v219, v[128:131] offset:512
	ds_write_b128 v219, v[132:135] offset:768
	ds_write_b128 v219, v[240:243] offset:1024
	ds_write_b128 v219, v[182:185] offset:1280
	ds_write_b128 v219, v[244:247] offset:1536
	ds_write_b128 v219, v[248:251] offset:1792
	ds_write_b128 v219, v[186:189] offset:2048
	ds_write_b128 v223, v[206:209]
	v_or_b32_e32 v6, v16, v55
	v_mov_b32_e32 v7, v17
	v_or_b32_e32 v16, v16, v54
	v_lshlrev_b64 v[12:13], 1, v[6:7]
	v_lshlrev_b64 v[22:23], 1, v[16:17]
	v_lshl_add_u64 v[56:57], v[56:57], 0, v[32:33]
	s_mov_b32 s7, 0x30000
	v_lshl_add_u64 v[6:7], s[70:71], 0, v[12:13]
	v_lshl_add_u64 v[8:9], s[12:13], 0, v[12:13]
	v_lshl_add_u64 v[10:11], s[14:15], 0, v[12:13]
	v_lshl_add_u64 v[14:15], s[16:17], 0, v[12:13]
	v_lshl_add_u64 v[18:19], s[18:19], 0, v[12:13]
	v_lshl_add_u64 v[16:17], s[70:71], 0, v[22:23]
	v_lshl_add_u64 v[20:21], s[12:13], 0, v[22:23]
	v_lshl_add_u64 v[24:25], s[14:15], 0, v[22:23]
	v_add_co_u32_e32 v32, vcc, s7, v56
	global_load_dwordx2 v[6:7], v[6:7], off
	s_nop 0
	global_load_dwordx2 v[8:9], v[8:9], off
	s_nop 0
	global_load_dwordx2 v[10:11], v[10:11], off
	s_nop 0
	global_load_dwordx2 v[12:13], v[14:15], off
	s_nop 0
	global_load_dwordx2 v[14:15], v[18:19], off
	s_nop 0
	global_load_dwordx2 v[18:19], v[16:17], off
	s_nop 0
	global_load_dwordx2 v[16:17], v[20:21], off
	s_nop 0
	global_load_dwordx2 v[20:21], v[24:25], off
	v_lshl_add_u64 v[24:25], s[16:17], 0, v[22:23]
	v_lshl_add_u64 v[22:23], s[18:19], 0, v[22:23]
	v_addc_co_u32_e32 v33, vcc, 0, v57, vcc
	global_load_dwordx2 v[24:25], v[24:25], off
	s_nop 0
	global_load_dwordx2 v[22:23], v[22:23], off
	v_cvt_f32_f16_sdwa v67, v50 dst_sel:DWORD dst_unused:UNUSED_PAD src0_sel:WORD_1
	global_load_dword v79, v[32:33], off
	v_cvt_f32_f16_e32 v66, v50
	v_cvt_f32_f16_sdwa v33, v52 dst_sel:DWORD dst_unused:UNUSED_PAD src0_sel:WORD_1
	v_cvt_f32_f16_e32 v32, v52
	v_cvt_f32_f16_sdwa v71, v53 dst_sel:DWORD dst_unused:UNUSED_PAD src0_sel:WORD_1
	v_cvt_f32_f16_e32 v70, v53
	s_waitcnt vmcnt(12)
	v_cvt_f32_f16_sdwa v75, v44 dst_sel:DWORD dst_unused:UNUSED_PAD src0_sel:WORD_1
	v_cvt_f32_f16_e32 v74, v44
	v_cvt_f32_f16_sdwa v53, v51 dst_sel:DWORD dst_unused:UNUSED_PAD src0_sel:WORD_1
	v_cvt_f32_f16_e32 v52, v51
	v_cvt_f32_f16_sdwa v93, v45 dst_sel:DWORD dst_unused:UNUSED_PAD src0_sel:WORD_1
	v_cvt_f32_f16_e32 v92, v45
	v_cvt_f32_f16_sdwa v65, v42 dst_sel:DWORD dst_unused:UNUSED_PAD src0_sel:WORD_1
	v_cvt_f32_f16_e32 v64, v42
	v_pk_add_f32 v[68:69], v[66:67], 1.0 op_sel_hi:[1,0] neg_lo:[1,0] neg_hi:[1,0]
	v_cvt_f32_f16_sdwa v73, v48 dst_sel:DWORD dst_unused:UNUSED_PAD src0_sel:WORD_1
	v_cvt_f32_f16_e32 v72, v48
	v_cvt_f32_f16_sdwa v83, v46 dst_sel:DWORD dst_unused:UNUSED_PAD src0_sel:WORD_1
	v_cvt_f32_f16_e32 v82, v46
	v_cvt_f32_f16_sdwa v67, v43 dst_sel:DWORD dst_unused:UNUSED_PAD src0_sel:WORD_1
	v_cvt_f32_f16_e32 v66, v43
	v_cvt_f32_f16_sdwa v89, v49 dst_sel:DWORD dst_unused:UNUSED_PAD src0_sel:WORD_1
	v_cvt_f32_f16_e32 v88, v49
	v_cvt_f32_f16_sdwa v91, v47 dst_sel:DWORD dst_unused:UNUSED_PAD src0_sel:WORD_1
	v_cvt_f32_f16_e32 v90, v47
	v_pk_add_f32 v[32:33], v[32:33], 1.0 op_sel_hi:[1,0] neg_lo:[1,0] neg_hi:[1,0]
	v_pk_add_f32 v[86:87], v[70:71], 1.0 op_sel_hi:[1,0] neg_lo:[1,0] neg_hi:[1,0]
	v_pk_mul_f32 v[84:85], v[32:33], v[74:75]
	v_pk_add_f32 v[70:71], v[52:53], 1.0 op_sel_hi:[1,0] neg_lo:[1,0] neg_hi:[1,0]
	v_pk_mul_f32 v[94:95], v[86:87], v[92:93]
	v_pk_mul_f32 v[50:51], v[68:69], v[84:85]
	v_pk_mul_f32 v[52:53], v[70:71], v[94:95]
	v_add_u32_e32 v80, v59, v62
	s_waitcnt lgkmcnt(0)
	s_cselect_b32 s62, 1, 0
	s_add_i32 s61, s61, 1
	s_waitcnt lgkmcnt(0)
	v_mov_b32_e32 v226, s61
	s_mov_b64 s[58:59], exec
	s_mov_b64 exec, 1
	ds_write_b32 v224, v226
	s_mov_b64 exec, s[58:59]
	s_cmp_lg_u32 s62, 0
	v_pk_mul_f32 v[42:43], v[68:69], v[72:73]
	v_pk_mul_f32 v[44:45], v[70:71], v[88:89]
	v_pk_mul_f32 v[46:47], v[68:69], v[82:83]
	v_pk_mul_f32 v[48:49], v[70:71], v[90:91]
	v_pk_mul_f32 v[68:69], v[68:69], v[32:33]
	v_pk_mul_f32 v[70:71], v[70:71], v[86:87]
	v_mov_b32_e32 v120, v64
	v_mov_b32_e32 v121, v46
	v_mov_b32_e32 v122, v65
	v_mov_b32_e32 v123, v47
	v_mov_b32_e32 v124, v42
	v_mov_b32_e32 v125, v50
	v_mov_b32_e32 v126, v43
	v_mov_b32_e32 v127, v51
	v_mov_b32_e32 v128, v66
	v_mov_b32_e32 v129, v48
	v_mov_b32_e32 v130, v67
	v_mov_b32_e32 v131, v49
	v_mov_b32_e32 v132, v44
	v_mov_b32_e32 v133, v52
	v_mov_b32_e32 v134, v45
	v_mov_b32_e32 v135, v53
	v_mov_b32_e32 v240, v68
	v_mov_b32_e32 v241, v69
	v_mov_b32_e32 v242, v70
	v_mov_b32_e32 v243, v71
	v_cvt_f32_f16_e32 v51, v38
	v_cvt_f32_f16_sdwa v53, v38 dst_sel:DWORD dst_unused:UNUSED_PAD src0_sel:WORD_1
	v_cvt_f32_f16_e32 v50, v40
	v_cvt_f32_f16_sdwa v52, v40 dst_sel:DWORD dst_unused:UNUSED_PAD src0_sel:WORD_1
	v_cvt_f32_f16_e32 v63, v39
	v_cvt_f32_f16_sdwa v65, v39 dst_sel:DWORD dst_unused:UNUSED_PAD src0_sel:WORD_1
	v_cvt_f32_f16_e32 v62, v41
	v_cvt_f32_f16_sdwa v64, v41 dst_sel:DWORD dst_unused:UNUSED_PAD src0_sel:WORD_1
	v_mov_b32_e32 v42, v51
	v_mov_b32_e32 v43, v53
	v_mov_b32_e32 v44, v50
	v_mov_b32_e32 v45, v52
	v_mov_b32_e32 v38, v63
	v_mov_b32_e32 v39, v65
	v_pk_mul_f32 v[42:43], v[32:33], v[42:43]
	v_pk_mul_f32 v[46:47], v[32:33], v[44:45]
	v_mov_b32_e32 v32, v83
	v_pk_mul_f32 v[44:45], v[86:87], v[38:39]
	v_mov_b32_e32 v38, v62
	v_mov_b32_e32 v39, v64
	v_pk_fma_f32 v[40:41], v[82:83], v[50:51], 0 op_sel_hi:[0,1,0]
	v_pk_mul_f32 v[48:49], v[86:87], v[38:39]
	v_mov_b32_e32 v182, v42
	v_mov_b32_e32 v183, v43
	v_mov_b32_e32 v184, v44
	v_mov_b32_e32 v185, v45
	v_mov_b32_e32 v244, v46
	v_mov_b32_e32 v245, v47
	v_mov_b32_e32 v246, v48
	v_mov_b32_e32 v247, v49
	v_pk_fma_f32 v[32:33], v[32:33], v[52:53], v[40:41] op_sel_hi:[0,1,1]
	v_mov_b32_e32 v40, v73
	v_pk_fma_f32 v[44:45], v[72:73], v[50:51], 0 op_sel_hi:[0,1,0]
	v_pk_fma_f32 v[40:41], v[40:41], v[52:53], v[44:45] op_sel_hi:[0,1,1]
	v_pk_fma_f32 v[44:45], v[84:85], v[50:51], 0 op_sel_hi:[0,1,0]
	v_pk_fma_f32 v[44:45], v[84:85], v[52:53], v[44:45] op_sel:[1,0,0]
	v_mov_b32_e32 v38, v91
	v_pk_fma_f32 v[32:33], v[90:91], v[62:63], v[32:33] op_sel_hi:[0,1,1]
	v_mov_b32_e32 v42, v89
	v_pk_fma_f32 v[40:41], v[88:89], v[62:63], v[40:41] op_sel_hi:[0,1,1]
	v_pk_fma_f32 v[44:45], v[94:95], v[62:63], v[44:45] op_sel_hi:[0,1,1]
	v_pk_fma_f32 v[32:33], v[38:39], v[64:65], v[32:33] op_sel_hi:[0,1,1]
	v_pk_fma_f32 v[40:41], v[42:43], v[64:65], v[40:41] op_sel_hi:[0,1,1]
	v_pk_fma_f32 v[44:45], v[94:95], v[64:65], v[44:45] op_sel:[1,0,0]
	v_cvt_f32_f16_e32 v49, v34
	v_cvt_f32_f16_sdwa v51, v34 dst_sel:DWORD dst_unused:UNUSED_PAD src0_sel:WORD_1
	v_cvt_f32_f16_e32 v63, v35
	v_cvt_f32_f16_sdwa v65, v35 dst_sel:DWORD dst_unused:UNUSED_PAD src0_sel:WORD_1
	v_cvt_f32_f16_e32 v48, v36
	v_cvt_f32_f16_sdwa v50, v36 dst_sel:DWORD dst_unused:UNUSED_PAD src0_sel:WORD_1
	v_cvt_f32_f16_e32 v62, v37
	v_cvt_f32_f16_sdwa v64, v37 dst_sel:DWORD dst_unused:UNUSED_PAD src0_sel:WORD_1
	v_mov_b32_e32 v34, v49
	v_mov_b32_e32 v35, v51
	v_mov_b32_e32 v36, v63
	v_mov_b32_e32 v37, v65
	v_mov_b32_e32 v248, v34
	v_mov_b32_e32 v249, v35
	v_mov_b32_e32 v250, v36
	v_mov_b32_e32 v251, v37
	v_mov_b32_e32 v34, v48
	v_mov_b32_e32 v35, v50
	v_mov_b32_e32 v36, v62
	v_mov_b32_e32 v37, v64
	v_mov_b32_e32 v52, v75
	v_mov_b32_e32 v186, v34
	v_mov_b32_e32 v187, v35
	v_mov_b32_e32 v188, v36
	v_mov_b32_e32 v189, v37
	v_pk_fma_f32 v[34:35], v[74:75], v[48:49], 0 op_sel_hi:[0,1,0]
	v_pk_fma_f32 v[34:35], v[52:53], v[50:51], v[34:35] op_sel_hi:[0,1,1]
	v_mov_b32_e32 v66, v93
	v_pk_fma_f32 v[34:35], v[92:93], v[62:63], v[34:35] op_sel_hi:[0,1,1]
	v_pk_fma_f32 v[34:35], v[66:67], v[64:65], v[34:35] op_sel_hi:[0,1,1]
	v_mov_b32_dpp v38, v32 row_ror:8 row_mask:0xf bank_mask:0xf bound_ctrl:1
	v_mov_b32_dpp v39, v33 row_ror:8 row_mask:0xf bank_mask:0xf bound_ctrl:1
	v_mov_b32_dpp v42, v40 row_ror:8 row_mask:0xf bank_mask:0xf bound_ctrl:1
	v_mov_b32_dpp v43, v41 row_ror:8 row_mask:0xf bank_mask:0xf bound_ctrl:1
	v_mov_b32_dpp v46, v44 row_ror:8 row_mask:0xf bank_mask:0xf bound_ctrl:1
	v_mov_b32_dpp v47, v45 row_ror:8 row_mask:0xf bank_mask:0xf bound_ctrl:1
	v_mov_b32_dpp v36, v34 row_ror:8 row_mask:0xf bank_mask:0xf bound_ctrl:1
	v_mov_b32_dpp v37, v35 row_ror:8 row_mask:0xf bank_mask:0xf bound_ctrl:1
	v_pk_add_f32 v[32:33], v[32:33], v[38:39]
	v_pk_add_f32 v[40:41], v[40:41], v[42:43]
	v_pk_add_f32 v[44:45], v[44:45], v[46:47]
	v_pk_add_f32 v[34:35], v[34:35], v[36:37]
	v_mov_b32_dpp v38, v32 row_ror:4 row_mask:0xf bank_mask:0xf bound_ctrl:1
	v_mov_b32_dpp v39, v33 row_ror:4 row_mask:0xf bank_mask:0xf bound_ctrl:1
	v_mov_b32_dpp v42, v40 row_ror:4 row_mask:0xf bank_mask:0xf bound_ctrl:1
	v_mov_b32_dpp v43, v41 row_ror:4 row_mask:0xf bank_mask:0xf bound_ctrl:1
	v_mov_b32_dpp v46, v44 row_ror:4 row_mask:0xf bank_mask:0xf bound_ctrl:1
	v_mov_b32_dpp v47, v45 row_ror:4 row_mask:0xf bank_mask:0xf bound_ctrl:1
	v_mov_b32_dpp v36, v34 row_ror:4 row_mask:0xf bank_mask:0xf bound_ctrl:1
	v_mov_b32_dpp v37, v35 row_ror:4 row_mask:0xf bank_mask:0xf bound_ctrl:1
	v_pk_add_f32 v[32:33], v[32:33], v[38:39]
	v_pk_add_f32 v[40:41], v[40:41], v[42:43]
	v_pk_add_f32 v[44:45], v[44:45], v[46:47]
	v_pk_add_f32 v[34:35], v[34:35], v[36:37]
	v_mov_b32_dpp v38, v32 row_ror:2 row_mask:0xf bank_mask:0xf bound_ctrl:1
	v_mov_b32_dpp v39, v33 row_ror:2 row_mask:0xf bank_mask:0xf bound_ctrl:1
	v_mov_b32_dpp v42, v40 row_ror:2 row_mask:0xf bank_mask:0xf bound_ctrl:1
	v_mov_b32_dpp v43, v41 row_ror:2 row_mask:0xf bank_mask:0xf bound_ctrl:1
	v_mov_b32_dpp v46, v44 row_ror:2 row_mask:0xf bank_mask:0xf bound_ctrl:1
	v_mov_b32_dpp v47, v45 row_ror:2 row_mask:0xf bank_mask:0xf bound_ctrl:1
	v_mov_b32_dpp v36, v34 row_ror:2 row_mask:0xf bank_mask:0xf bound_ctrl:1
	v_mov_b32_dpp v37, v35 row_ror:2 row_mask:0xf bank_mask:0xf bound_ctrl:1
	v_pk_add_f32 v[32:33], v[32:33], v[38:39]
	v_pk_add_f32 v[40:41], v[40:41], v[42:43]
	v_pk_add_f32 v[44:45], v[44:45], v[46:47]
	v_pk_add_f32 v[34:35], v[34:35], v[36:37]
	v_mov_b32_dpp v38, v32 row_ror:1 row_mask:0xf bank_mask:0xf bound_ctrl:1
	v_mov_b32_dpp v39, v33 row_ror:1 row_mask:0xf bank_mask:0xf bound_ctrl:1
	v_mov_b32_dpp v42, v40 row_ror:1 row_mask:0xf bank_mask:0xf bound_ctrl:1
	v_mov_b32_dpp v43, v41 row_ror:1 row_mask:0xf bank_mask:0xf bound_ctrl:1
	v_mov_b32_dpp v46, v44 row_ror:1 row_mask:0xf bank_mask:0xf bound_ctrl:1
	v_mov_b32_dpp v47, v45 row_ror:1 row_mask:0xf bank_mask:0xf bound_ctrl:1
	v_mov_b32_dpp v36, v34 row_ror:1 row_mask:0xf bank_mask:0xf bound_ctrl:1
	v_mov_b32_dpp v37, v35 row_ror:1 row_mask:0xf bank_mask:0xf bound_ctrl:1
	s_cselect_b32 s62, 1, 0
	s_sub_i32 s63, s61, 1

.Lst_go_i3:
	s_cmp_lg_u32 s62, 0
	s_and_saveexec_b64 s[20:21], s[0:1]
	s_cbranch_execz .LBB0_663
	v_pk_add_f32 v[38:39], v[32:33], v[38:39]
	v_pk_add_f32 v[32:33], v[40:41], v[42:43]
	s_mov_b32 s10, 0x3d800000
	v_pk_mul_f32 v[40:41], v[32:33], s[10:11] op_sel_hi:[1,0]
	v_pk_add_f32 v[32:33], v[44:45], v[46:47]
	v_pk_add_f32 v[34:35], v[34:35], v[36:37]
	v_pk_mul_f32 v[32:33], v[32:33], s[10:11] op_sel_hi:[1,0]
	v_pk_mul_f32 v[34:35], v[34:35], s[10:11] op_sel_hi:[1,0]
	ds_write_b128 v77, v[38:41] offset:36864
	ds_write_b128 v77, v[32:35] offset:36880
.LBB0_663:
	s_or_b64 exec, exec, s[20:21]
	s_add_u32 s20, s78, 0xf000000
	s_addc_u32 s21, s79, 0
	s_add_u32 s7, s20, s6
	s_addc_u32 s9, s21, 0
	s_add_u32 s22, s7, s8
	s_addc_u32 s23, s9, 0
	v_mov_b32_e32 v3, 0
	s_waitcnt vmcnt(11)
	v_cvt_f32_f16_sdwa v35, v61 dst_sel:DWORD dst_unused:UNUSED_PAD src0_sel:WORD_1
	v_cvt_f32_f16_e32 v34, v61
	v_lshl_add_u64 v[32:33], s[22:23], 0, v[2:3]
	s_mov_b64 s[22:23], 0x20000
	v_lshl_add_u64 v[38:39], v[28:29], 0, s[22:23]
	v_or_b32_e32 v28, v38, v55
	v_mov_b32_e32 v29, v39
	v_or_b32_e32 v38, v38, v54
	v_lshlrev_b64 v[30:31], 12, v[30:31]
	ds_write_b64 v1, v[34:35] offset:37632
	ds_read_b128 v[198:201], v216 offset:36864
	ds_read_b128 v[202:205], v216 offset:36880
	ds_read2_b32 v[206:207], v220 offset1:16
	s_waitcnt lgkmcnt(0)
	v_mul_f32_e32 v210, 0x41800000, v200
	v_mul_f32_e32 v211, 0x41800000, v202
	v_mul_f32_e32 v212, 0x41800000, v204
	v_fma_f32 v213, -v204, v199, v203
	v_fma_f32 v121, -v198, v120, v121
	v_fma_f32 v124, -v210, v120, v124
	v_fma_f32 v125, -v211, v120, v125
	v_fma_f32 v123, -v198, v122, v123
	v_fma_f32 v126, -v210, v122, v126
	v_fma_f32 v127, -v211, v122, v127
	v_fma_f32 v129, -v198, v128, v129
	v_fma_f32 v132, -v210, v128, v132
	v_fma_f32 v133, -v211, v128, v133
	v_fma_f32 v131, -v198, v130, v131
	v_fma_f32 v134, -v210, v130, v134
	v_fma_f32 v135, -v211, v130, v135
	v_fma_f32 v182, -v199, v186, v182
	v_fma_f32 v183, -v199, v187, v183
	v_fma_f32 v184, -v199, v188, v184
	v_fma_f32 v185, -v199, v189, v185
	v_fma_f32 v125, -v212, v121, v125
	v_fma_f32 v127, -v212, v123, v127
	v_fma_f32 v133, -v212, v129, v133
	v_fma_f32 v135, -v212, v131, v135
	v_mul_f32_e32 v208, v206, v201
	v_mul_f32_e32 v209, v206, v213
	ds_write_b128 v218, v[120:123]
	v_fmac_f32_e32 v209, v207, v205
	ds_write_b128 v218, v[124:127] offset:256
	ds_write_b128 v218, v[128:131] offset:512
	ds_write_b128 v218, v[132:135] offset:768
	ds_write_b128 v218, v[240:243] offset:1024
	ds_write_b128 v218, v[182:185] offset:1280
	ds_write_b128 v218, v[244:247] offset:1536
	ds_write_b128 v218, v[248:251] offset:1792
	ds_write_b128 v218, v[186:189] offset:2048
	ds_write_b128 v222, v[206:209]
	v_lshlrev_b64 v[34:35], 1, v[28:29]
	v_lshlrev_b64 v[44:45], 1, v[38:39]
	s_mov_b32 s7, 0x40000
	v_lshl_add_u64 v[52:53], v[32:33], 0, v[30:31]
	v_lshl_add_u64 v[28:29], s[70:71], 0, v[34:35]
	v_lshl_add_u64 v[30:31], s[12:13], 0, v[34:35]
	v_lshl_add_u64 v[32:33], s[14:15], 0, v[34:35]
	v_lshl_add_u64 v[36:37], s[16:17], 0, v[34:35]
	v_lshl_add_u64 v[40:41], s[18:19], 0, v[34:35]
	v_lshl_add_u64 v[38:39], s[70:71], 0, v[44:45]
	v_lshl_add_u64 v[42:43], s[12:13], 0, v[44:45]
	v_lshl_add_u64 v[46:47], s[14:15], 0, v[44:45]
	v_add_co_u32_e32 v48, vcc, s7, v56
	global_load_dwordx2 v[28:29], v[28:29], off
	s_nop 0
	global_load_dwordx2 v[30:31], v[30:31], off
	s_nop 0
	global_load_dwordx2 v[32:33], v[32:33], off
	s_nop 0
	global_load_dwordx2 v[34:35], v[36:37], off
	s_nop 0
	global_load_dwordx2 v[36:37], v[40:41], off
	s_nop 0
	global_load_dwordx2 v[40:41], v[38:39], off
	s_nop 0
	global_load_dwordx2 v[38:39], v[42:43], off
	s_nop 0
	global_load_dwordx2 v[42:43], v[46:47], off
	v_lshl_add_u64 v[46:47], s[16:17], 0, v[44:45]
	v_lshl_add_u64 v[44:45], s[18:19], 0, v[44:45]
	v_addc_co_u32_e32 v49, vcc, 0, v57, vcc
	global_load_dwordx2 v[46:47], v[46:47], off
	s_nop 0
	global_load_dwordx2 v[44:45], v[44:45], off
	v_or_b32_e32 v3, v60, v58
	global_load_dword v81, v[48:49], off
	v_lshlrev_b32_e32 v3, 6, v3
	v_add_u32_e32 v3, 0, v3
	v_bfe_u32 v177, v152, 4, 1
	v_sub_u32_e32 v176, 0, v177
	v_lshlrev_b32_e32 v178, 6, v177
	v_sub_u32_e32 v179, 64, v178
	v_bfe_u32 v177, v152, 1, 2
	v_add_u32_e32 v180, 0, v177
	v_and_b32_e32 v180, 3, v180
	v_lshlrev_b32_e32 v180, 4, v180
	v_add3_u32 v160, v3, v178, v180
	v_add3_u32 v164, v3, v179, v180
	v_add_u32_e32 v180, 1, v177
	v_and_b32_e32 v180, 3, v180
	v_lshlrev_b32_e32 v180, 4, v180
	v_add3_u32 v161, v3, v178, v180
	v_add3_u32 v165, v3, v179, v180
	v_add_u32_e32 v180, 2, v177
	v_and_b32_e32 v180, 3, v180
	v_lshlrev_b32_e32 v180, 4, v180
	v_add3_u32 v162, v3, v178, v180
	v_add3_u32 v166, v3, v179, v180
	v_add_u32_e32 v180, 3, v177
	v_and_b32_e32 v180, 3, v180
	v_lshlrev_b32_e32 v180, 4, v180
	v_add3_u32 v163, v3, v178, v180
	v_add3_u32 v167, v3, v179, v180
	v_add_u32_e32 v168, 0x11b00, v160
	v_add_u32_e32 v169, 0x11b00, v161
	v_add_u32_e32 v170, 0x11b00, v162
	v_add_u32_e32 v171, 0x11b00, v163
	v_add_u32_e32 v172, 0x11b00, v164
	v_add_u32_e32 v173, 0x11b00, v165
	v_add_u32_e32 v174, 0x11b00, v166
	v_add_u32_e32 v175, 0x11b00, v167
	ds_read_b128 v[120:123], v160 offset:39680
	ds_read_b128 v[124:127], v161 offset:39680
	ds_read_b128 v[128:131], v162 offset:39680
	ds_read_b128 v[132:135], v163 offset:39680
	ds_read_b128 v[136:139], v164 offset:39680
	ds_read_b128 v[140:143], v165 offset:39680
	ds_read_b128 v[144:147], v166 offset:39680
	ds_read_b128 v[148:151], v167 offset:39680
	s_movk_i32 s7, 0x7fff
	v_mov_b32_e32 v82, 1
	s_mov_b32 s9, 0xffff0000
	s_lshl_b32 s10, s2, 20
	s_and_b32 s10, s10, 0x4000000
	s_waitcnt lgkmcnt(0)
	v_pk_add_f32 v[120:121], v[120:121], v[124:125]
	v_pk_add_f32 v[122:123], v[122:123], v[126:127]
	v_pk_add_f32 v[128:129], v[128:129], v[132:133]
	v_pk_add_f32 v[130:131], v[130:131], v[134:135]
	v_pk_add_f32 v[120:121], v[120:121], v[128:129]
	v_pk_add_f32 v[122:123], v[122:123], v[130:131]
	v_pk_add_f32 v[120:121], v[120:121], v[122:123]
	v_add_f32_e32 v120, v120, v121
	v_pk_add_f32 v[136:137], v[136:137], v[140:141]
	v_pk_add_f32 v[138:139], v[138:139], v[142:143]
	v_pk_add_f32 v[144:145], v[144:145], v[148:149]
	v_pk_add_f32 v[146:147], v[146:147], v[150:151]
	v_pk_add_f32 v[136:137], v[136:137], v[144:145]
	v_pk_add_f32 v[138:139], v[138:139], v[146:147]
	v_pk_add_f32 v[136:137], v[136:137], v[138:139]
	v_add_f32_e32 v136, v136, v137
	v_bfi_b32 v49, v176, v136, v120
	v_bfi_b32 v48, v176, v120, v136
	v_and_b32_sdwa v50, v49, v82 dst_sel:DWORD dst_unused:UNUSED_PAD src0_sel:WORD_1 src1_sel:DWORD
	v_and_b32_sdwa v51, v48, v82 dst_sel:DWORD dst_unused:UNUSED_PAD src0_sel:WORD_1 src1_sel:DWORD
	v_add3_u32 v49, v49, v50, s7
	v_add3_u32 v48, v48, v51, s7
	v_lshrrev_b32_e32 v49, 16, v49
	v_and_or_b32 v48, v48, s9, v49
	global_store_dword v[52:53], v48, off
	v_lshlrev_b64 v[48:49], 12, v[4:5]
	v_lshl_add_u64 v[48:49], s[10:11], 0, v[48:49]
	s_lshl_b32 s10, s25, 5
	v_and_b32_e32 v50, 7, v153
	s_and_b32 s14, s10, 0x780
	v_lshlrev_b32_e32 v52, 2, v50
	v_lshlrev_b64 v[50:51], 11, v[4:5]
	v_or_b32_e32 v48, s14, v48
	s_and_b32 s15, s24, 0x60
	v_or_b32_e32 v50, s14, v50
	v_or3_b32 v48, v48, s15, v52
	v_or3_b32 v50, v50, s15, v52
	v_lshlrev_b64 v[52:53], 11, v[26:27]
	v_lshl_add_u64 v[48:49], s[78:79], 0, v[48:49]
	s_mov_b64 s[12:13], 0xf040000
	s_lshl_b32 s10, s2, 19
	v_lshl_or_b32 v52, v55, 1, v52
	v_lshl_add_u64 v[48:49], v[48:49], 0, s[12:13]
	s_and_b32 s10, s10, 0x2000000
	v_lshl_add_u64 v[50:51], s[70:71], 0, v[50:51]
	v_lshl_add_u64 v[26:27], s[70:71], 0, v[52:53]
	v_lshl_add_u64 v[52:53], s[78:79], 0, v[52:53]
	s_mov_b32 s12, 0x3d800000
	s_mov_b64 s[14:15], 0x40000
	s_mov_b32 s13, s11
	s_cselect_b32 s62, 1, 0
	s_add_i32 s61, s61, 1
	s_waitcnt lgkmcnt(0)
	v_mov_b32_e32 v226, s61
	s_mov_b64 s[58:59], exec
	s_mov_b64 exec, 1
	ds_write_b32 v224, v226
	s_mov_b64 exec, s[58:59]
	s_cmp_lg_u32 s62, 0
	s_branch .LBB0_665
.LBB0_664:
	ds_read_b128 v[120:123], v160 offset:39680
	ds_read_b128 v[124:127], v161 offset:39680
	ds_read_b128 v[128:131], v162 offset:39680
	ds_read_b128 v[132:135], v163 offset:39680
	ds_read_b128 v[136:139], v164 offset:39680
	ds_read_b128 v[140:143], v165 offset:39680
	ds_read_b128 v[144:147], v166 offset:39680
	ds_read_b128 v[148:151], v167 offset:39680
	v_lshl_add_u64 v[50:51], v[50:51], 0, s[22:23]
	v_lshl_add_u64 v[26:27], v[26:27], 0, s[22:23]
	v_lshl_add_u64 v[52:53], v[52:53], 0, s[22:23]
	s_and_b64 vcc, exec, s[16:17]
	s_nop 0
	s_waitcnt lgkmcnt(0)
	v_pk_add_f32 v[120:121], v[120:121], v[124:125]
	v_pk_add_f32 v[122:123], v[122:123], v[126:127]
	v_pk_add_f32 v[128:129], v[128:129], v[132:133]
	v_pk_add_f32 v[130:131], v[130:131], v[134:135]
	v_pk_add_f32 v[120:121], v[120:121], v[128:129]
	v_pk_add_f32 v[122:123], v[122:123], v[130:131]
	v_pk_add_f32 v[120:121], v[120:121], v[122:123]
	v_add_f32_e32 v120, v120, v121
	v_pk_add_f32 v[136:137], v[136:137], v[140:141]
	v_pk_add_f32 v[138:139], v[138:139], v[142:143]
	v_pk_add_f32 v[144:145], v[144:145], v[148:149]
	v_pk_add_f32 v[146:147], v[146:147], v[150:151]
	v_pk_add_f32 v[136:137], v[136:137], v[144:145]
	v_pk_add_f32 v[138:139], v[138:139], v[146:147]
	v_pk_add_f32 v[136:137], v[136:137], v[138:139]
	v_add_f32_e32 v136, v136, v137
	v_bfi_b32 v55, v176, v136, v120
	v_bfi_b32 v54, v176, v120, v136
	v_and_b32_sdwa v56, v55, v82 dst_sel:DWORD dst_unused:UNUSED_PAD src0_sel:WORD_1 src1_sel:DWORD
	v_and_b32_sdwa v57, v54, v82 dst_sel:DWORD dst_unused:UNUSED_PAD src0_sel:WORD_1 src1_sel:DWORD
	v_add3_u32 v55, v55, v56, s7
	v_add3_u32 v54, v54, v57, s7
	v_lshrrev_b32_e32 v55, 16, v55
	v_and_or_b32 v54, v54, s9, v55
	global_store_dword v[48:49], v54, off
	v_lshl_add_u64 v[48:49], v[48:49], 0, s[14:15]
	s_cselect_b32 s62, 1, 0
	s_add_i32 s61, s61, 1
	s_waitcnt lgkmcnt(0)
	v_mov_b32_e32 v226, s61
	s_mov_b64 s[58:59], exec
	s_mov_b64 exec, 1
	ds_write_b32 v224, v226
	s_mov_b64 exec, s[58:59]
	s_cmp_lg_u32 s62, 0
	s_cbranch_vccnz .LBB0_675
.LBB0_665:
	s_waitcnt vmcnt(11)
	v_cvt_f32_f16_sdwa v59, v8 dst_sel:DWORD dst_unused:UNUSED_PAD src0_sel:WORD_1
	v_cvt_f32_f16_e32 v58, v8
	s_waitcnt vmcnt(10)
	v_cvt_f32_f16_sdwa v57, v16 dst_sel:DWORD dst_unused:UNUSED_PAD src0_sel:WORD_1
	v_cvt_f32_f16_e32 v56, v16
	v_cvt_f32_f16_sdwa v61, v9 dst_sel:DWORD dst_unused:UNUSED_PAD src0_sel:WORD_1
	v_pk_add_f32 v[70:71], v[58:59], 1.0 op_sel_hi:[1,0] neg_lo:[1,0] neg_hi:[1,0]
	v_cvt_f32_f16_sdwa v59, v17 dst_sel:DWORD dst_unused:UNUSED_PAD src0_sel:WORD_1
	v_cvt_f32_f16_e32 v58, v17
	v_cvt_f32_f16_e32 v60, v9
	s_waitcnt vmcnt(9)
	v_cvt_f32_f16_sdwa v87, v18 dst_sel:DWORD dst_unused:UNUSED_PAD src0_sel:WORD_1
	v_cvt_f32_f16_e32 v86, v18
	s_waitcnt vmcnt(3)
	v_cvt_f32_f16_sdwa v89, v24 dst_sel:DWORD dst_unused:UNUSED_PAD src0_sel:WORD_1
	v_cvt_f32_f16_e32 v88, v24
	v_cvt_f32_f16_sdwa v97, v25 dst_sel:DWORD dst_unused:UNUSED_PAD src0_sel:WORD_1
	v_cvt_f32_f16_e32 v96, v25
	v_cvt_f32_f16_sdwa v99, v19 dst_sel:DWORD dst_unused:UNUSED_PAD src0_sel:WORD_1
	v_cvt_f32_f16_e32 v98, v19
	v_cvt_f32_f16_sdwa v55, v12 dst_sel:DWORD dst_unused:UNUSED_PAD src0_sel:WORD_1
	v_cvt_f32_f16_e32 v54, v12
	v_pk_add_f32 v[74:75], v[56:57], 1.0 op_sel_hi:[1,0] neg_lo:[1,0] neg_hi:[1,0]
	v_cvt_f32_f16_sdwa v85, v6 dst_sel:DWORD dst_unused:UNUSED_PAD src0_sel:WORD_1
	v_cvt_f32_f16_e32 v84, v6
	v_cvt_f32_f16_sdwa v57, v13 dst_sel:DWORD dst_unused:UNUSED_PAD src0_sel:WORD_1
	v_cvt_f32_f16_e32 v56, v13
	v_cvt_f32_f16_sdwa v95, v7 dst_sel:DWORD dst_unused:UNUSED_PAD src0_sel:WORD_1
	v_cvt_f32_f16_e32 v94, v7
	v_pk_add_f32 v[92:93], v[58:59], 1.0 op_sel_hi:[1,0] neg_lo:[1,0] neg_hi:[1,0]
	v_pk_add_f32 v[72:73], v[60:61], 1.0 op_sel_hi:[1,0] neg_lo:[1,0] neg_hi:[1,0]
	v_pk_mul_f32 v[90:91], v[74:75], v[86:87]
	v_pk_mul_f32 v[62:63], v[70:71], v[88:89]
	v_pk_mul_f32 v[64:65], v[72:73], v[96:97]
	v_pk_mul_f32 v[100:101], v[92:93], v[98:99]
	v_pk_mul_f32 v[58:59], v[70:71], v[84:85]
	v_pk_mul_f32 v[60:61], v[72:73], v[94:95]
	v_pk_mul_f32 v[66:67], v[70:71], v[90:91]
	v_pk_mul_f32 v[68:69], v[72:73], v[100:101]
	v_pk_mul_f32 v[70:71], v[70:71], v[74:75]
	v_pk_mul_f32 v[72:73], v[72:73], v[92:93]
	v_mov_b32_e32 v120, v54
	v_mov_b32_e32 v121, v62
	v_mov_b32_e32 v122, v55
	v_mov_b32_e32 v123, v63
	v_mov_b32_e32 v124, v58
	v_mov_b32_e32 v125, v66
	v_mov_b32_e32 v126, v59
	v_mov_b32_e32 v127, v67
	v_mov_b32_e32 v128, v56
	v_mov_b32_e32 v129, v64
	v_mov_b32_e32 v130, v57
	v_mov_b32_e32 v131, v65
	v_mov_b32_e32 v132, v60
	v_mov_b32_e32 v133, v68
	v_mov_b32_e32 v134, v61
	v_mov_b32_e32 v135, v69
	v_mov_b32_e32 v240, v70
	v_mov_b32_e32 v241, v71
	v_mov_b32_e32 v242, v72
	v_mov_b32_e32 v243, v73
	v_cvt_f32_f16_e32 v62, v14
	v_cvt_f32_f16_sdwa v64, v14 dst_sel:DWORD dst_unused:UNUSED_PAD src0_sel:WORD_1
	v_cvt_f32_f16_e32 v63, v10
	v_cvt_f32_f16_sdwa v65, v10 dst_sel:DWORD dst_unused:UNUSED_PAD src0_sel:WORD_1
	v_cvt_f32_f16_e32 v69, v11
	v_cvt_f32_f16_sdwa v71, v11 dst_sel:DWORD dst_unused:UNUSED_PAD src0_sel:WORD_1
	v_cvt_f32_f16_e32 v68, v15
	v_cvt_f32_f16_sdwa v70, v15 dst_sel:DWORD dst_unused:UNUSED_PAD src0_sel:WORD_1
	v_mov_b32_e32 v56, v62
	v_mov_b32_e32 v57, v64
	v_mov_b32_e32 v54, v63
	v_mov_b32_e32 v55, v65
	v_pk_mul_f32 v[58:59], v[74:75], v[56:57]
	v_mov_b32_e32 v56, v69
	v_mov_b32_e32 v57, v71
	v_pk_mul_f32 v[54:55], v[74:75], v[54:55]
	v_pk_mul_f32 v[56:57], v[92:93], v[56:57]
	v_mov_b32_e32 v60, v68
	v_mov_b32_e32 v61, v70
	v_mov_b32_e32 v66, v89
	v_pk_mul_f32 v[60:61], v[92:93], v[60:61]
	v_mov_b32_e32 v182, v54
	v_mov_b32_e32 v183, v55
	v_mov_b32_e32 v184, v56
	v_mov_b32_e32 v185, v57
	v_mov_b32_e32 v244, v58
	v_mov_b32_e32 v245, v59
	v_mov_b32_e32 v246, v60
	v_mov_b32_e32 v247, v61
	v_pk_fma_f32 v[54:55], v[88:89], v[62:63], 0 op_sel_hi:[0,1,0]
	v_pk_fma_f32 v[54:55], v[66:67], v[64:65], v[54:55] op_sel_hi:[0,1,1]
	v_mov_b32_e32 v58, v85
	v_pk_fma_f32 v[66:67], v[84:85], v[62:63], 0 op_sel_hi:[0,1,0]
	v_pk_fma_f32 v[62:63], v[90:91], v[62:63], 0 op_sel_hi:[0,1,0]
	v_pk_fma_f32 v[58:59], v[58:59], v[64:65], v[66:67] op_sel_hi:[0,1,1]
	v_pk_fma_f32 v[62:63], v[90:91], v[64:65], v[62:63] op_sel:[1,0,0]
	v_mov_b32_e32 v72, v97
	v_pk_fma_f32 v[54:55], v[96:97], v[68:69], v[54:55] op_sel_hi:[0,1,1]
	v_mov_b32_e32 v60, v95
	v_pk_fma_f32 v[58:59], v[94:95], v[68:69], v[58:59] op_sel_hi:[0,1,1]
	v_pk_fma_f32 v[62:63], v[100:101], v[68:69], v[62:63] op_sel_hi:[0,1,1]
	v_pk_fma_f32 v[54:55], v[72:73], v[70:71], v[54:55] op_sel_hi:[0,1,1]
	v_pk_fma_f32 v[58:59], v[60:61], v[70:71], v[58:59] op_sel_hi:[0,1,1]
	v_pk_fma_f32 v[62:63], v[100:101], v[70:71], v[62:63] op_sel:[1,0,0]
	v_cvt_f32_f16_e32 v71, v20
	v_cvt_f32_f16_sdwa v73, v20 dst_sel:DWORD dst_unused:UNUSED_PAD src0_sel:WORD_1
	v_cvt_f32_f16_e32 v85, v21
	v_cvt_f32_f16_sdwa v89, v21 dst_sel:DWORD dst_unused:UNUSED_PAD src0_sel:WORD_1
	s_waitcnt vmcnt(13)
	v_cvt_f32_f16_e32 v70, v22
	v_cvt_f32_f16_sdwa v72, v22 dst_sel:DWORD dst_unused:UNUSED_PAD src0_sel:WORD_1
	v_cvt_f32_f16_e32 v84, v23
	v_cvt_f32_f16_sdwa v88, v23 dst_sel:DWORD dst_unused:UNUSED_PAD src0_sel:WORD_1
	v_mov_b32_e32 v66, v71
	v_mov_b32_e32 v67, v73
	v_mov_b32_e32 v68, v85
	v_mov_b32_e32 v69, v89
	v_mov_b32_e32 v248, v66
	v_mov_b32_e32 v249, v67
	v_mov_b32_e32 v250, v68
	v_mov_b32_e32 v251, v69
	v_mov_b32_e32 v66, v70
	v_mov_b32_e32 v67, v72
	v_mov_b32_e32 v68, v84
	v_mov_b32_e32 v69, v88
	v_mov_b32_e32 v74, v87
	v_mov_b32_e32 v186, v66
	v_mov_b32_e32 v187, v67
	v_mov_b32_e32 v188, v68
	v_mov_b32_e32 v189, v69
	v_pk_fma_f32 v[66:67], v[86:87], v[70:71], 0 op_sel_hi:[0,1,0]
	v_pk_fma_f32 v[66:67], v[74:75], v[72:73], v[66:67] op_sel_hi:[0,1,1]
	v_mov_b32_e32 v90, v99
	v_pk_fma_f32 v[66:67], v[98:99], v[84:85], v[66:67] op_sel_hi:[0,1,1]
	v_pk_fma_f32 v[66:67], v[90:91], v[88:89], v[66:67] op_sel_hi:[0,1,1]
	v_mov_b32_dpp v56, v54 row_ror:8 row_mask:0xf bank_mask:0xf bound_ctrl:1
	v_mov_b32_dpp v57, v55 row_ror:8 row_mask:0xf bank_mask:0xf bound_ctrl:1
	v_mov_b32_dpp v60, v58 row_ror:8 row_mask:0xf bank_mask:0xf bound_ctrl:1
	v_mov_b32_dpp v61, v59 row_ror:8 row_mask:0xf bank_mask:0xf bound_ctrl:1
	v_mov_b32_dpp v64, v62 row_ror:8 row_mask:0xf bank_mask:0xf bound_ctrl:1
	v_mov_b32_dpp v65, v63 row_ror:8 row_mask:0xf bank_mask:0xf bound_ctrl:1
	v_mov_b32_dpp v68, v66 row_ror:8 row_mask:0xf bank_mask:0xf bound_ctrl:1
	v_mov_b32_dpp v69, v67 row_ror:8 row_mask:0xf bank_mask:0xf bound_ctrl:1
	v_pk_add_f32 v[54:55], v[54:55], v[56:57]
	v_pk_add_f32 v[58:59], v[58:59], v[60:61]
	v_pk_add_f32 v[62:63], v[62:63], v[64:65]
	v_pk_add_f32 v[66:67], v[66:67], v[68:69]
	v_mov_b32_dpp v56, v54 row_ror:4 row_mask:0xf bank_mask:0xf bound_ctrl:1
	v_mov_b32_dpp v57, v55 row_ror:4 row_mask:0xf bank_mask:0xf bound_ctrl:1
	v_mov_b32_dpp v60, v58 row_ror:4 row_mask:0xf bank_mask:0xf bound_ctrl:1
	v_mov_b32_dpp v61, v59 row_ror:4 row_mask:0xf bank_mask:0xf bound_ctrl:1
	v_mov_b32_dpp v64, v62 row_ror:4 row_mask:0xf bank_mask:0xf bound_ctrl:1
	v_mov_b32_dpp v65, v63 row_ror:4 row_mask:0xf bank_mask:0xf bound_ctrl:1
	v_mov_b32_dpp v68, v66 row_ror:4 row_mask:0xf bank_mask:0xf bound_ctrl:1
	v_mov_b32_dpp v69, v67 row_ror:4 row_mask:0xf bank_mask:0xf bound_ctrl:1
	v_pk_add_f32 v[54:55], v[54:55], v[56:57]
	v_pk_add_f32 v[58:59], v[58:59], v[60:61]
	v_pk_add_f32 v[62:63], v[62:63], v[64:65]
	v_pk_add_f32 v[66:67], v[66:67], v[68:69]
	v_mov_b32_dpp v56, v54 row_ror:2 row_mask:0xf bank_mask:0xf bound_ctrl:1
	v_mov_b32_dpp v57, v55 row_ror:2 row_mask:0xf bank_mask:0xf bound_ctrl:1
	v_mov_b32_dpp v60, v58 row_ror:2 row_mask:0xf bank_mask:0xf bound_ctrl:1
	v_mov_b32_dpp v61, v59 row_ror:2 row_mask:0xf bank_mask:0xf bound_ctrl:1
	v_mov_b32_dpp v64, v62 row_ror:2 row_mask:0xf bank_mask:0xf bound_ctrl:1
	v_mov_b32_dpp v65, v63 row_ror:2 row_mask:0xf bank_mask:0xf bound_ctrl:1
	v_mov_b32_dpp v68, v66 row_ror:2 row_mask:0xf bank_mask:0xf bound_ctrl:1
	v_mov_b32_dpp v69, v67 row_ror:2 row_mask:0xf bank_mask:0xf bound_ctrl:1
	v_pk_add_f32 v[54:55], v[54:55], v[56:57]
	v_pk_add_f32 v[58:59], v[58:59], v[60:61]
	v_pk_add_f32 v[62:63], v[62:63], v[64:65]
	v_pk_add_f32 v[66:67], v[66:67], v[68:69]
	v_mov_b32_dpp v56, v54 row_ror:1 row_mask:0xf bank_mask:0xf bound_ctrl:1
	v_mov_b32_dpp v57, v55 row_ror:1 row_mask:0xf bank_mask:0xf bound_ctrl:1
	v_mov_b32_dpp v60, v58 row_ror:1 row_mask:0xf bank_mask:0xf bound_ctrl:1
	v_mov_b32_dpp v61, v59 row_ror:1 row_mask:0xf bank_mask:0xf bound_ctrl:1
	v_mov_b32_dpp v64, v62 row_ror:1 row_mask:0xf bank_mask:0xf bound_ctrl:1
	v_mov_b32_dpp v65, v63 row_ror:1 row_mask:0xf bank_mask:0xf bound_ctrl:1
	v_mov_b32_dpp v68, v66 row_ror:1 row_mask:0xf bank_mask:0xf bound_ctrl:1
	v_mov_b32_dpp v69, v67 row_ror:1 row_mask:0xf bank_mask:0xf bound_ctrl:1
	s_cselect_b32 s62, 1, 0
	s_sub_i32 s63, s61, 1

.Lst_go_i4:
	s_cmp_lg_u32 s62, 0
	s_and_saveexec_b64 s[16:17], s[0:1]
	s_cbranch_execz .LBB0_667
	v_pk_add_f32 v[54:55], v[54:55], v[56:57]
	v_pk_add_f32 v[56:57], v[58:59], v[60:61]
	v_add_u32_e32 v58, 0x1ab00, v77
	v_pk_mul_f32 v[56:57], v[56:57], s[12:13] op_sel_hi:[1,0]
	ds_write_b128 v58, v[54:57]
	v_pk_add_f32 v[54:55], v[62:63], v[64:65]
	v_pk_add_f32 v[56:57], v[66:67], v[68:69]
	v_pk_mul_f32 v[54:55], v[54:55], s[12:13] op_sel_hi:[1,0]
	v_pk_mul_f32 v[56:57], v[56:57], s[12:13] op_sel_hi:[1,0]
	ds_write_b128 v58, v[54:57] offset:16
.LBB0_667:
	s_or_b64 exec, exec, s[16:17]
	s_waitcnt vmcnt(2)
	v_cvt_f32_f16_sdwa v55, v79 dst_sel:DWORD dst_unused:UNUSED_PAD src0_sel:WORD_1
	v_cvt_f32_f16_e32 v54, v79
	s_add_i32 s13, s13, 2
	s_cmpk_gt_u32 s13, 0x1fc
	v_lshl_add_u64 v[58:59], v[26:27], 0, s[10:11]
	ds_write_b64 v78, v[54:55]
	ds_read_b128 v[198:201], v217 offset:36864
	ds_read_b128 v[202:205], v217 offset:36880
	ds_read2_b32 v[206:207], v221 offset1:16
	s_waitcnt lgkmcnt(0)
	v_mul_f32_e32 v210, 0x41800000, v200
	v_mul_f32_e32 v211, 0x41800000, v202
	v_mul_f32_e32 v212, 0x41800000, v204
	v_fma_f32 v213, -v204, v199, v203
	v_fma_f32 v121, -v198, v120, v121
	v_fma_f32 v124, -v210, v120, v124
	v_fma_f32 v125, -v211, v120, v125
	v_fma_f32 v123, -v198, v122, v123
	v_fma_f32 v126, -v210, v122, v126
	v_fma_f32 v127, -v211, v122, v127
	v_fma_f32 v129, -v198, v128, v129
	v_fma_f32 v132, -v210, v128, v132
	v_fma_f32 v133, -v211, v128, v133
	v_fma_f32 v131, -v198, v130, v131
	v_fma_f32 v134, -v210, v130, v134
	v_fma_f32 v135, -v211, v130, v135
	v_fma_f32 v182, -v199, v186, v182
	v_fma_f32 v183, -v199, v187, v183
	v_fma_f32 v184, -v199, v188, v184
	v_fma_f32 v185, -v199, v189, v185
	v_fma_f32 v125, -v212, v121, v125
	v_fma_f32 v127, -v212, v123, v127
	v_fma_f32 v133, -v212, v129, v133
	v_fma_f32 v135, -v212, v131, v135
	v_mul_f32_e32 v208, v206, v201
	v_mul_f32_e32 v209, v206, v213
	ds_write_b128 v219, v[120:123]
	v_fmac_f32_e32 v209, v207, v205
	ds_write_b128 v219, v[124:127] offset:256
	ds_write_b128 v219, v[128:131] offset:512
	ds_write_b128 v219, v[132:135] offset:768
	ds_write_b128 v219, v[240:243] offset:1024
	ds_write_b128 v219, v[182:185] offset:1280
	ds_write_b128 v219, v[244:247] offset:1536
	ds_write_b128 v219, v[248:251] offset:1792
	ds_write_b128 v219, v[186:189] offset:2048
	ds_write_b128 v223, v[206:209]
	v_lshl_add_u64 v[56:57], v[52:53], 0, s[10:11]
	v_lshl_add_u64 v[54:55], v[50:51], 0, s[10:11]
	s_cbranch_scc1 .LBB0_669
	v_add_co_u32_e32 v10, vcc, 0x50000, v58
	s_nop 1
	v_addc_co_u32_e32 v11, vcc, 0, v59, vcc
	v_add_co_u32_e32 v12, vcc, 0x4050000, v58
	s_nop 1
	v_addc_co_u32_e32 v13, vcc, 0, v59, vcc
	v_add_co_u32_e32 v14, vcc, 0x8050000, v58
	s_nop 1
	v_addc_co_u32_e32 v15, vcc, 0, v59, vcc
	v_add_co_u32_e32 v24, vcc, 0x30050000, v56
	s_nop 1
	v_addc_co_u32_e32 v25, vcc, 0, v57, vcc
	v_add_co_u32_e32 v22, vcc, 0x34050000, v56
	s_nop 1
	v_addc_co_u32_e32 v23, vcc, 0, v57, vcc
	global_load_dwordx2 v[6:7], v[10:11], off
	global_load_dwordx2 v[8:9], v[12:13], off
	global_load_dwordx2 v[16:17], v[12:13], off offset:2048
	global_load_dwordx2 v[18:19], v[10:11], off offset:2048
	s_nop 0
	global_load_dwordx2 v[10:11], v[14:15], off
	global_load_dwordx2 v[20:21], v[14:15], off offset:2048
	global_load_dwordx2 v[12:13], v[24:25], off
	s_nop 0
	global_load_dwordx2 v[14:15], v[22:23], off
	s_nop 0
	global_load_dwordx2 v[22:23], v[22:23], off offset:2048
	s_nop 0
	global_load_dwordx2 v[24:25], v[24:25], off offset:2048
	v_add_co_u32_e32 v60, vcc, 0xc050000, v54
	s_nop 1
	v_addc_co_u32_e32 v61, vcc, 0, v55, vcc
	global_load_dword v79, v[60:61], off
.LBB0_669:
	ds_read_b128 v[120:123], v168 offset:39680
	ds_read_b128 v[124:127], v169 offset:39680
	ds_read_b128 v[128:131], v170 offset:39680
	ds_read_b128 v[132:135], v171 offset:39680
	ds_read_b128 v[136:139], v172 offset:39680
	ds_read_b128 v[140:143], v173 offset:39680
	ds_read_b128 v[144:147], v174 offset:39680
	ds_read_b128 v[148:151], v175 offset:39680
	s_cmpk_gt_u32 s13, 0x1fd
	s_cselect_b64 s[16:17], -1, 0
	s_nop 0
	s_nop 0
	s_nop 0
	s_waitcnt lgkmcnt(0)
	v_pk_add_f32 v[120:121], v[120:121], v[124:125]
	v_pk_add_f32 v[122:123], v[122:123], v[126:127]
	v_pk_add_f32 v[128:129], v[128:129], v[132:133]
	v_pk_add_f32 v[130:131], v[130:131], v[134:135]
	v_pk_add_f32 v[120:121], v[120:121], v[128:129]
	v_pk_add_f32 v[122:123], v[122:123], v[130:131]
	v_pk_add_f32 v[120:121], v[120:121], v[122:123]
	v_add_f32_e32 v120, v120, v121
	v_pk_add_f32 v[136:137], v[136:137], v[140:141]
	v_pk_add_f32 v[138:139], v[138:139], v[142:143]
	v_pk_add_f32 v[144:145], v[144:145], v[148:149]
	v_pk_add_f32 v[146:147], v[146:147], v[150:151]
	v_pk_add_f32 v[136:137], v[136:137], v[144:145]
	v_pk_add_f32 v[138:139], v[138:139], v[146:147]
	v_pk_add_f32 v[136:137], v[136:137], v[138:139]
	v_add_f32_e32 v136, v136, v137
	v_bfi_b32 v61, v176, v136, v120
	v_bfi_b32 v60, v176, v120, v136
	v_and_b32_sdwa v62, v61, v82 dst_sel:DWORD dst_unused:UNUSED_PAD src0_sel:WORD_1 src1_sel:DWORD
	v_and_b32_sdwa v63, v60, v82 dst_sel:DWORD dst_unused:UNUSED_PAD src0_sel:WORD_1 src1_sel:DWORD
	v_add3_u32 v61, v61, v62, s7
	v_add3_u32 v60, v60, v63, s7
	v_lshrrev_b32_e32 v61, 16, v61
	v_and_or_b32 v62, v60, s9, v61
	v_add_co_u32_e32 v60, vcc, 0xfffe0000, v48
	s_nop 1
	v_addc_co_u32_e32 v61, vcc, -1, v49, vcc
	s_and_b64 vcc, exec, s[16:17]
	global_store_dword v[60:61], v62, off
	s_cselect_b32 s62, 1, 0
	s_add_i32 s61, s61, 1
	s_waitcnt lgkmcnt(0)
	v_mov_b32_e32 v226, s61
	s_mov_b64 s[58:59], exec
	s_mov_b64 exec, 1
	ds_write_b32 v224, v226
	s_mov_b64 exec, s[58:59]
	s_cmp_lg_u32 s62, 0
	s_cbranch_vccnz .Lst_skip5
	s_waitcnt vmcnt(11)
	v_cvt_f32_f16_sdwa v65, v30 dst_sel:DWORD dst_unused:UNUSED_PAD src0_sel:WORD_1
	v_cvt_f32_f16_e32 v64, v30
	s_waitcnt vmcnt(6)
	v_cvt_f32_f16_sdwa v63, v38 dst_sel:DWORD dst_unused:UNUSED_PAD src0_sel:WORD_1
	v_cvt_f32_f16_e32 v62, v38
	v_cvt_f32_f16_sdwa v67, v31 dst_sel:DWORD dst_unused:UNUSED_PAD src0_sel:WORD_1
	v_pk_add_f32 v[84:85], v[64:65], 1.0 op_sel_hi:[1,0] neg_lo:[1,0] neg_hi:[1,0]
	v_cvt_f32_f16_sdwa v65, v39 dst_sel:DWORD dst_unused:UNUSED_PAD src0_sel:WORD_1
	v_cvt_f32_f16_e32 v64, v39
	v_cvt_f32_f16_e32 v66, v31
	v_cvt_f32_f16_sdwa v93, v40 dst_sel:DWORD dst_unused:UNUSED_PAD src0_sel:WORD_1
	v_cvt_f32_f16_e32 v92, v40
	s_waitcnt vmcnt(4)
	v_cvt_f32_f16_sdwa v95, v46 dst_sel:DWORD dst_unused:UNUSED_PAD src0_sel:WORD_1
	v_cvt_f32_f16_e32 v94, v46
	v_cvt_f32_f16_sdwa v103, v47 dst_sel:DWORD dst_unused:UNUSED_PAD src0_sel:WORD_1
	v_cvt_f32_f16_e32 v102, v47
	v_cvt_f32_f16_sdwa v105, v41 dst_sel:DWORD dst_unused:UNUSED_PAD src0_sel:WORD_1
	v_cvt_f32_f16_e32 v104, v41
	v_cvt_f32_f16_sdwa v61, v34 dst_sel:DWORD dst_unused:UNUSED_PAD src0_sel:WORD_1
	v_cvt_f32_f16_e32 v60, v34
	v_pk_add_f32 v[88:89], v[62:63], 1.0 op_sel_hi:[1,0] neg_lo:[1,0] neg_hi:[1,0]
	v_cvt_f32_f16_sdwa v91, v28 dst_sel:DWORD dst_unused:UNUSED_PAD src0_sel:WORD_1
	v_cvt_f32_f16_e32 v90, v28
	v_cvt_f32_f16_sdwa v63, v35 dst_sel:DWORD dst_unused:UNUSED_PAD src0_sel:WORD_1
	v_cvt_f32_f16_e32 v62, v35
	v_cvt_f32_f16_sdwa v101, v29 dst_sel:DWORD dst_unused:UNUSED_PAD src0_sel:WORD_1
	v_cvt_f32_f16_e32 v100, v29
	v_pk_add_f32 v[98:99], v[64:65], 1.0 op_sel_hi:[1,0] neg_lo:[1,0] neg_hi:[1,0]
	v_pk_add_f32 v[86:87], v[66:67], 1.0 op_sel_hi:[1,0] neg_lo:[1,0] neg_hi:[1,0]
	v_pk_mul_f32 v[96:97], v[88:89], v[92:93]
	v_pk_mul_f32 v[68:69], v[84:85], v[94:95]
	v_pk_mul_f32 v[70:71], v[86:87], v[102:103]
	v_pk_mul_f32 v[106:107], v[98:99], v[104:105]
	v_pk_mul_f32 v[64:65], v[84:85], v[90:91]
	v_pk_mul_f32 v[66:67], v[86:87], v[100:101]
	v_pk_mul_f32 v[72:73], v[84:85], v[96:97]
	v_pk_mul_f32 v[74:75], v[86:87], v[106:107]
	v_pk_mul_f32 v[84:85], v[84:85], v[88:89]
	v_pk_mul_f32 v[86:87], v[86:87], v[98:99]
	v_mov_b32_e32 v120, v60
	v_mov_b32_e32 v121, v68
	v_mov_b32_e32 v122, v61
	v_mov_b32_e32 v123, v69
	v_mov_b32_e32 v124, v64
	v_mov_b32_e32 v125, v72
	v_mov_b32_e32 v126, v65
	v_mov_b32_e32 v127, v73
	v_mov_b32_e32 v128, v62
	v_mov_b32_e32 v129, v70
	v_mov_b32_e32 v130, v63
	v_mov_b32_e32 v131, v71
	v_mov_b32_e32 v132, v66
	v_mov_b32_e32 v133, v74
	v_mov_b32_e32 v134, v67
	v_mov_b32_e32 v135, v75
	v_mov_b32_e32 v240, v84
	v_mov_b32_e32 v241, v85
	v_mov_b32_e32 v242, v86
	v_mov_b32_e32 v243, v87
	v_cvt_f32_f16_e32 v68, v36
	v_cvt_f32_f16_sdwa v70, v36 dst_sel:DWORD dst_unused:UNUSED_PAD src0_sel:WORD_1
	v_cvt_f32_f16_e32 v69, v32
	v_cvt_f32_f16_sdwa v71, v32 dst_sel:DWORD dst_unused:UNUSED_PAD src0_sel:WORD_1
	v_cvt_f32_f16_e32 v75, v33
	v_cvt_f32_f16_sdwa v85, v33 dst_sel:DWORD dst_unused:UNUSED_PAD src0_sel:WORD_1
	v_cvt_f32_f16_e32 v74, v37
	v_cvt_f32_f16_sdwa v84, v37 dst_sel:DWORD dst_unused:UNUSED_PAD src0_sel:WORD_1
	v_mov_b32_e32 v62, v68
	v_mov_b32_e32 v63, v70
	v_mov_b32_e32 v60, v69
	v_mov_b32_e32 v61, v71
	v_pk_mul_f32 v[64:65], v[88:89], v[62:63]
	v_mov_b32_e32 v62, v75
	v_mov_b32_e32 v63, v85
	v_pk_mul_f32 v[60:61], v[88:89], v[60:61]
	v_pk_mul_f32 v[62:63], v[98:99], v[62:63]
	v_mov_b32_e32 v66, v74
	v_mov_b32_e32 v67, v84
	v_mov_b32_e32 v72, v95
	v_pk_mul_f32 v[66:67], v[98:99], v[66:67]
	v_mov_b32_e32 v182, v60
	v_mov_b32_e32 v183, v61
	v_mov_b32_e32 v184, v62
	v_mov_b32_e32 v185, v63
	v_mov_b32_e32 v244, v64
	v_mov_b32_e32 v245, v65
	v_mov_b32_e32 v246, v66
	v_mov_b32_e32 v247, v67
	v_pk_fma_f32 v[60:61], v[94:95], v[68:69], 0 op_sel_hi:[0,1,0]
	v_pk_fma_f32 v[60:61], v[72:73], v[70:71], v[60:61] op_sel_hi:[0,1,1]
	v_mov_b32_e32 v64, v91
	v_pk_fma_f32 v[72:73], v[90:91], v[68:69], 0 op_sel_hi:[0,1,0]
	v_pk_fma_f32 v[68:69], v[96:97], v[68:69], 0 op_sel_hi:[0,1,0]
	v_pk_fma_f32 v[64:65], v[64:65], v[70:71], v[72:73] op_sel_hi:[0,1,1]
	v_pk_fma_f32 v[68:69], v[96:97], v[70:71], v[68:69] op_sel:[1,0,0]
	v_mov_b32_e32 v86, v103
	v_pk_fma_f32 v[60:61], v[102:103], v[74:75], v[60:61] op_sel_hi:[0,1,1]
	v_mov_b32_e32 v66, v101
	v_pk_fma_f32 v[64:65], v[100:101], v[74:75], v[64:65] op_sel_hi:[0,1,1]
	v_pk_fma_f32 v[68:69], v[106:107], v[74:75], v[68:69] op_sel_hi:[0,1,1]
	v_pk_fma_f32 v[60:61], v[86:87], v[84:85], v[60:61] op_sel_hi:[0,1,1]
	v_pk_fma_f32 v[64:65], v[66:67], v[84:85], v[64:65] op_sel_hi:[0,1,1]
	v_pk_fma_f32 v[68:69], v[106:107], v[84:85], v[68:69] op_sel:[1,0,0]
	v_cvt_f32_f16_e32 v85, v42
	v_cvt_f32_f16_sdwa v87, v42 dst_sel:DWORD dst_unused:UNUSED_PAD src0_sel:WORD_1
	v_cvt_f32_f16_e32 v91, v43
	v_cvt_f32_f16_sdwa v95, v43 dst_sel:DWORD dst_unused:UNUSED_PAD src0_sel:WORD_1
	s_waitcnt vmcnt(3)
	v_cvt_f32_f16_e32 v84, v44
	v_cvt_f32_f16_sdwa v86, v44 dst_sel:DWORD dst_unused:UNUSED_PAD src0_sel:WORD_1
	v_cvt_f32_f16_e32 v90, v45
	v_cvt_f32_f16_sdwa v94, v45 dst_sel:DWORD dst_unused:UNUSED_PAD src0_sel:WORD_1
	v_mov_b32_e32 v72, v85
	v_mov_b32_e32 v73, v87
	v_mov_b32_e32 v74, v91
	v_mov_b32_e32 v75, v95
	v_mov_b32_e32 v248, v72
	v_mov_b32_e32 v249, v73
	v_mov_b32_e32 v250, v74
	v_mov_b32_e32 v251, v75
	v_mov_b32_e32 v72, v84
	v_mov_b32_e32 v73, v86
	v_mov_b32_e32 v74, v90
	v_mov_b32_e32 v75, v94
	v_mov_b32_e32 v88, v93
	v_mov_b32_e32 v186, v72
	v_mov_b32_e32 v187, v73
	v_mov_b32_e32 v188, v74
	v_mov_b32_e32 v189, v75
	v_pk_fma_f32 v[72:73], v[92:93], v[84:85], 0 op_sel_hi:[0,1,0]
	v_pk_fma_f32 v[72:73], v[88:89], v[86:87], v[72:73] op_sel_hi:[0,1,1]
	v_mov_b32_e32 v96, v105
	v_pk_fma_f32 v[72:73], v[104:105], v[90:91], v[72:73] op_sel_hi:[0,1,1]
	v_pk_fma_f32 v[72:73], v[96:97], v[94:95], v[72:73] op_sel_hi:[0,1,1]
	v_mov_b32_dpp v62, v60 row_ror:8 row_mask:0xf bank_mask:0xf bound_ctrl:1
	v_mov_b32_dpp v63, v61 row_ror:8 row_mask:0xf bank_mask:0xf bound_ctrl:1
	v_mov_b32_dpp v66, v64 row_ror:8 row_mask:0xf bank_mask:0xf bound_ctrl:1
	v_mov_b32_dpp v67, v65 row_ror:8 row_mask:0xf bank_mask:0xf bound_ctrl:1
	v_mov_b32_dpp v70, v68 row_ror:8 row_mask:0xf bank_mask:0xf bound_ctrl:1
	v_mov_b32_dpp v71, v69 row_ror:8 row_mask:0xf bank_mask:0xf bound_ctrl:1
	v_mov_b32_dpp v74, v72 row_ror:8 row_mask:0xf bank_mask:0xf bound_ctrl:1
	v_mov_b32_dpp v75, v73 row_ror:8 row_mask:0xf bank_mask:0xf bound_ctrl:1
	v_pk_add_f32 v[60:61], v[60:61], v[62:63]
	v_pk_add_f32 v[64:65], v[64:65], v[66:67]
	v_pk_add_f32 v[68:69], v[68:69], v[70:71]
	v_pk_add_f32 v[72:73], v[72:73], v[74:75]
	v_mov_b32_dpp v62, v60 row_ror:4 row_mask:0xf bank_mask:0xf bound_ctrl:1
	v_mov_b32_dpp v63, v61 row_ror:4 row_mask:0xf bank_mask:0xf bound_ctrl:1
	v_mov_b32_dpp v66, v64 row_ror:4 row_mask:0xf bank_mask:0xf bound_ctrl:1
	v_mov_b32_dpp v67, v65 row_ror:4 row_mask:0xf bank_mask:0xf bound_ctrl:1
	v_mov_b32_dpp v70, v68 row_ror:4 row_mask:0xf bank_mask:0xf bound_ctrl:1
	v_mov_b32_dpp v71, v69 row_ror:4 row_mask:0xf bank_mask:0xf bound_ctrl:1
	v_mov_b32_dpp v74, v72 row_ror:4 row_mask:0xf bank_mask:0xf bound_ctrl:1
	v_mov_b32_dpp v75, v73 row_ror:4 row_mask:0xf bank_mask:0xf bound_ctrl:1
	v_pk_add_f32 v[60:61], v[60:61], v[62:63]
	v_pk_add_f32 v[64:65], v[64:65], v[66:67]
	v_pk_add_f32 v[68:69], v[68:69], v[70:71]
	v_pk_add_f32 v[72:73], v[72:73], v[74:75]
	v_mov_b32_dpp v62, v60 row_ror:2 row_mask:0xf bank_mask:0xf bound_ctrl:1
	v_mov_b32_dpp v63, v61 row_ror:2 row_mask:0xf bank_mask:0xf bound_ctrl:1
	v_mov_b32_dpp v66, v64 row_ror:2 row_mask:0xf bank_mask:0xf bound_ctrl:1
	v_mov_b32_dpp v67, v65 row_ror:2 row_mask:0xf bank_mask:0xf bound_ctrl:1
	v_mov_b32_dpp v70, v68 row_ror:2 row_mask:0xf bank_mask:0xf bound_ctrl:1
	v_mov_b32_dpp v71, v69 row_ror:2 row_mask:0xf bank_mask:0xf bound_ctrl:1
	v_mov_b32_dpp v74, v72 row_ror:2 row_mask:0xf bank_mask:0xf bound_ctrl:1
	v_mov_b32_dpp v75, v73 row_ror:2 row_mask:0xf bank_mask:0xf bound_ctrl:1
	v_pk_add_f32 v[60:61], v[60:61], v[62:63]
	v_pk_add_f32 v[64:65], v[64:65], v[66:67]
	v_pk_add_f32 v[68:69], v[68:69], v[70:71]
	v_pk_add_f32 v[72:73], v[72:73], v[74:75]
	v_mov_b32_dpp v62, v60 row_ror:1 row_mask:0xf bank_mask:0xf bound_ctrl:1
	v_mov_b32_dpp v63, v61 row_ror:1 row_mask:0xf bank_mask:0xf bound_ctrl:1
	v_mov_b32_dpp v66, v64 row_ror:1 row_mask:0xf bank_mask:0xf bound_ctrl:1
	v_mov_b32_dpp v67, v65 row_ror:1 row_mask:0xf bank_mask:0xf bound_ctrl:1
	v_mov_b32_dpp v70, v68 row_ror:1 row_mask:0xf bank_mask:0xf bound_ctrl:1
	v_mov_b32_dpp v71, v69 row_ror:1 row_mask:0xf bank_mask:0xf bound_ctrl:1
	v_mov_b32_dpp v74, v72 row_ror:1 row_mask:0xf bank_mask:0xf bound_ctrl:1
	v_mov_b32_dpp v75, v73 row_ror:1 row_mask:0xf bank_mask:0xf bound_ctrl:1
	s_cselect_b32 s62, 1, 0
	s_sub_i32 s63, s61, 1

.Lst_go_i5:
	s_cmp_lg_u32 s62, 0
	s_and_saveexec_b64 s[18:19], s[0:1]
	s_cbranch_execz .LBB0_672
	v_pk_add_f32 v[60:61], v[60:61], v[62:63]
	v_pk_add_f32 v[62:63], v[64:65], v[66:67]
	s_nop 0
	v_pk_mul_f32 v[62:63], v[62:63], s[12:13] op_sel_hi:[1,0]
	ds_write_b128 v77, v[60:63] offset:36864
	v_pk_add_f32 v[60:61], v[68:69], v[70:71]
	v_pk_add_f32 v[62:63], v[72:73], v[74:75]
	v_pk_mul_f32 v[60:61], v[60:61], s[12:13] op_sel_hi:[1,0]
	v_pk_mul_f32 v[62:63], v[62:63], s[12:13] op_sel_hi:[1,0]
	ds_write_b128 v77, v[60:63] offset:36880
.LBB0_672:
	s_or_b64 exec, exec, s[18:19]
	s_waitcnt vmcnt(2)
	v_cvt_f32_f16_sdwa v61, v81 dst_sel:DWORD dst_unused:UNUSED_PAD src0_sel:WORD_1
	v_cvt_f32_f16_e32 v60, v81
	ds_write_b64 v1, v[60:61] offset:37632
	ds_read_b128 v[198:201], v216 offset:36864
	ds_read_b128 v[202:205], v216 offset:36880
	ds_read2_b32 v[206:207], v220 offset1:16
	s_waitcnt lgkmcnt(0)
	v_mul_f32_e32 v210, 0x41800000, v200
	v_mul_f32_e32 v211, 0x41800000, v202
	v_mul_f32_e32 v212, 0x41800000, v204
	v_fma_f32 v213, -v204, v199, v203
	v_fma_f32 v121, -v198, v120, v121
	v_fma_f32 v124, -v210, v120, v124
	v_fma_f32 v125, -v211, v120, v125
	v_fma_f32 v123, -v198, v122, v123
	v_fma_f32 v126, -v210, v122, v126
	v_fma_f32 v127, -v211, v122, v127
	v_fma_f32 v129, -v198, v128, v129
	v_fma_f32 v132, -v210, v128, v132
	v_fma_f32 v133, -v211, v128, v133
	v_fma_f32 v131, -v198, v130, v131
	v_fma_f32 v134, -v210, v130, v134
	v_fma_f32 v135, -v211, v130, v135
	v_fma_f32 v182, -v199, v186, v182
	v_fma_f32 v183, -v199, v187, v183
	v_fma_f32 v184, -v199, v188, v184
	v_fma_f32 v185, -v199, v189, v185
	v_fma_f32 v125, -v212, v121, v125
	v_fma_f32 v127, -v212, v123, v127
	v_fma_f32 v133, -v212, v129, v133
	v_fma_f32 v135, -v212, v131, v135
	v_mul_f32_e32 v208, v206, v201
	v_mul_f32_e32 v209, v206, v213
	ds_write_b128 v218, v[120:123]
	v_fmac_f32_e32 v209, v207, v205
	ds_write_b128 v218, v[124:127] offset:256
	ds_write_b128 v218, v[128:131] offset:512
	ds_write_b128 v218, v[132:135] offset:768
	ds_write_b128 v218, v[240:243] offset:1024
	ds_write_b128 v218, v[182:185] offset:1280
	ds_write_b128 v218, v[244:247] offset:1536
	ds_write_b128 v218, v[248:251] offset:1792
	ds_write_b128 v218, v[186:189] offset:2048
	ds_write_b128 v222, v[206:209]

.Lst_skip5:
	s_cselect_b32 s62, 1, 0
	s_sub_i32 s63, s61, 1

.Lst_go_ex:
	s_cmp_lg_u32 s62, 0
	ds_read_b128 v[120:123], v168 offset:39680
	ds_read_b128 v[124:127], v169 offset:39680
	ds_read_b128 v[128:131], v170 offset:39680
	ds_read_b128 v[132:135], v171 offset:39680
	ds_read_b128 v[136:139], v172 offset:39680
	ds_read_b128 v[140:143], v173 offset:39680
	ds_read_b128 v[144:147], v174 offset:39680
	ds_read_b128 v[148:151], v175 offset:39680
	s_waitcnt vmcnt(11)
	s_waitcnt vmcnt(6)
	s_waitcnt vmcnt(5)
	s_waitcnt vmcnt(3)
	v_mov_b32_e32 v1, 1
	v_lshl_add_u64 v[4:5], v[4:5], 0, s[4:5]
	s_movk_i32 s0, 0x7fff
	v_lshlrev_b64 v[4:5], 12, v[4:5]
	s_mov_b32 s7, 0
	s_waitcnt lgkmcnt(0)
	v_pk_add_f32 v[120:121], v[120:121], v[124:125]
	v_pk_add_f32 v[122:123], v[122:123], v[126:127]
	v_pk_add_f32 v[128:129], v[128:129], v[132:133]
	v_pk_add_f32 v[130:131], v[130:131], v[134:135]
	v_pk_add_f32 v[120:121], v[120:121], v[128:129]
	v_pk_add_f32 v[122:123], v[122:123], v[130:131]
	v_pk_add_f32 v[120:121], v[120:121], v[122:123]
	v_add_f32_e32 v120, v120, v121
	v_pk_add_f32 v[136:137], v[136:137], v[140:141]
	v_pk_add_f32 v[138:139], v[138:139], v[142:143]
	v_pk_add_f32 v[144:145], v[144:145], v[148:149]
	v_pk_add_f32 v[146:147], v[146:147], v[150:151]
	v_pk_add_f32 v[136:137], v[136:137], v[144:145]
	v_pk_add_f32 v[138:139], v[138:139], v[146:147]
	v_pk_add_f32 v[136:137], v[136:137], v[138:139]
	v_add_f32_e32 v136, v136, v137
	v_bfi_b32 v7, v176, v136, v120
	v_bfi_b32 v6, v176, v120, v136
	v_and_b32_sdwa v3, v7, v1 dst_sel:DWORD dst_unused:UNUSED_PAD src0_sel:WORD_1 src1_sel:DWORD
	v_and_b32_sdwa v1, v6, v1 dst_sel:DWORD dst_unused:UNUSED_PAD src0_sel:WORD_1 src1_sel:DWORD
	v_add3_u32 v3, v7, v3, s0
	v_lshl_add_u64 v[4:5], s[20:21], 0, v[4:5]
	v_add3_u32 v1, v6, v1, s0
	v_lshrrev_b32_e32 v3, 16, v3
	s_mov_b32 s0, 0xffff0000
	v_lshl_add_u64 v[4:5], v[4:5], 0, s[6:7]
	s_mov_b32 s9, s7
	v_and_or_b32 v1, v1, s0, v3
	v_lshl_add_u64 v[4:5], v[4:5], 0, s[8:9]
	v_mov_b32_e32 v3, 0
	v_lshl_add_u64 v[2:3], v[4:5], 0, v[2:3]
	v_add_co_u32_e32 v2, vcc, 0x3fe0000, v2
	s_nop 1
	v_addc_co_u32_e32 v3, vcc, 0, v3, vcc
	global_store_dword v[2:3], v1, off
